# GEMM loops: s_setprio 1 issued before the pre-MFMA barrier and s_setprio 0 after the post-MFMA barrier (barrier release is followed directly by the first MFMA; the last MFMA directly by the barrier)
# baseline (speedup 1.0000x reference)
.LBB0_145:
	s_add_u32 s27, s50, 0x100
	s_addc_u32 s56, s51, 0
	s_mov_b32 s57, -2
	s_waitcnt lgkmcnt(0)
	ds_read_b128 v[128:131], v188
	ds_read_b128 v[132:135], v188 offset:1024
	ds_read_b128 v[136:139], v188 offset:2048
	ds_read_b128 v[140:143], v188 offset:3072
	ds_read_b128 v[144:147], v189
	ds_read_b128 v[148:151], v189 offset:1024
	ds_read_b128 v[176:179], v189 offset:2048
	ds_read_b128 v[180:183], v189 offset:3072
	s_add_u32 s50, s48, 0x100
	s_addc_u32 s51, s49, 0
	s_cmp_eq_u32 s57, 28
	s_cselect_b32 s55, s21, s51
	s_cselect_b32 s54, s20, s50
	s_cselect_b32 s53, s23, s56
	s_cselect_b32 s52, s22, s27
	v_lshl_add_u64 v[184:185], s[48:49], 0, v[170:171]
	s_add_i32 m0, s60, 0xc000
	ds_read_b128 v[194:197], v190
	ds_read_b128 v[198:201], v190 offset:1024
	ds_read_b128 v[202:205], v190 offset:2048
	ds_read_b128 v[206:209], v190 offset:3072
	ds_read_b128 v[210:213], v190 offset:4096
	ds_read_b128 v[214:217], v190 offset:5120
	ds_read_b128 v[218:221], v190 offset:6144
	ds_read_b128 v[222:225], v190 offset:7168
	global_load_lds_dwordx4 v[184:185], off
	v_lshl_add_u64 v[184:185], s[48:49], 0, v[172:173]
	s_add_i32 m0, s60, 0xe000
	s_nop 0
	global_load_lds_dwordx4 v[184:185], off
	s_waitcnt vmcnt(8)
	s_waitcnt lgkmcnt(0)
	s_waitcnt lgkmcnt(0)
	s_setprio 1
	s_barrier
	v_mfma_f32_16x16x32_bf16 v[120:123], v[128:131], v[194:197], 0
	v_mfma_f32_16x16x32_bf16 v[124:127], v[136:139], v[194:197], 0
	v_mfma_f32_16x16x32_bf16 v[108:111], v[128:131], v[202:205], 0
	v_mfma_f32_16x16x32_bf16 v[104:107], v[136:139], v[202:205], 0
	v_mfma_f32_16x16x32_bf16 v[92:95], v[128:131], v[210:213], 0
	v_mfma_f32_16x16x32_bf16 v[88:91], v[136:139], v[210:213], 0
	v_mfma_f32_16x16x32_bf16 v[76:79], v[128:131], v[218:221], 0
	v_mfma_f32_16x16x32_bf16 v[72:75], v[136:139], v[218:221], 0
	v_mfma_f32_16x16x32_bf16 v[120:123], v[132:135], v[198:201], v[120:123]
	v_mfma_f32_16x16x32_bf16 v[124:127], v[140:143], v[198:201], v[124:127]
	v_mfma_f32_16x16x32_bf16 v[108:111], v[132:135], v[206:209], v[108:111]
	v_mfma_f32_16x16x32_bf16 v[104:107], v[140:143], v[206:209], v[104:107]
	v_mfma_f32_16x16x32_bf16 v[92:95], v[132:135], v[214:217], v[92:95]
	v_mfma_f32_16x16x32_bf16 v[88:91], v[140:143], v[214:217], v[88:91]
	v_mfma_f32_16x16x32_bf16 v[76:79], v[132:135], v[222:225], v[76:79]
	v_mfma_f32_16x16x32_bf16 v[72:75], v[140:143], v[222:225], v[72:75]
	s_setprio 0
	s_setprio 1
	v_mfma_f32_16x16x32_bf16 v[112:115], v[144:147], v[194:197], 0
	v_mfma_f32_16x16x32_bf16 v[116:119], v[176:179], v[194:197], 0
	v_mfma_f32_16x16x32_bf16 v[100:103], v[144:147], v[202:205], 0
	v_mfma_f32_16x16x32_bf16 v[96:99], v[176:179], v[202:205], 0
	v_mfma_f32_16x16x32_bf16 v[84:87], v[144:147], v[210:213], 0
	v_mfma_f32_16x16x32_bf16 v[80:83], v[176:179], v[210:213], 0
	v_mfma_f32_16x16x32_bf16 v[68:71], v[144:147], v[218:221], 0
	v_mfma_f32_16x16x32_bf16 v[64:67], v[176:179], v[218:221], 0
	v_mfma_f32_16x16x32_bf16 v[112:115], v[148:151], v[198:201], v[112:115]
	v_mfma_f32_16x16x32_bf16 v[116:119], v[180:183], v[198:201], v[116:119]
	v_mfma_f32_16x16x32_bf16 v[100:103], v[148:151], v[206:209], v[100:103]
	v_mfma_f32_16x16x32_bf16 v[96:99], v[180:183], v[206:209], v[96:99]
	v_mfma_f32_16x16x32_bf16 v[84:87], v[148:151], v[214:217], v[84:87]
	v_mfma_f32_16x16x32_bf16 v[80:83], v[180:183], v[214:217], v[80:83]
	v_mfma_f32_16x16x32_bf16 v[68:71], v[148:151], v[222:225], v[68:71]
	v_mfma_f32_16x16x32_bf16 v[64:67], v[180:183], v[222:225], v[64:67]
	s_barrier
	s_setprio 0
	s_add_i32 s48, s71, s3
	v_lshl_add_u64 v[184:185], s[52:53], 0, v[154:155]
	s_mov_b32 m0, s48
	ds_read_b128 v[194:197], v190 offset:16384
	ds_read_b128 v[198:201], v190 offset:17408
	ds_read_b128 v[202:205], v190 offset:18432
	ds_read_b128 v[206:209], v190 offset:19456
	ds_read_b128 v[210:213], v190 offset:20480
	ds_read_b128 v[214:217], v190 offset:21504
	ds_read_b128 v[218:221], v190 offset:22528
	ds_read_b128 v[222:225], v190 offset:23552
	global_load_lds_dwordx4 v[184:185], off
	s_add_i32 m0, s48, 0x2000
	s_add_u32 s48, s52, 0x80000
	v_lshl_add_u64 v[226:227], s[52:53], 0, v[158:159]
	s_addc_u32 s49, s53, 0
	s_add_i32 s58, s72, s3
	global_load_lds_dwordx4 v[226:227], off
	v_lshl_add_u64 v[228:229], s[48:49], 0, v[154:155]
	s_mov_b32 m0, s58
	v_lshl_add_u64 v[230:231], s[54:55], 0, v[156:157]
	global_load_lds_dwordx4 v[228:229], off
	v_lshl_add_u64 v[228:229], s[48:49], 0, v[158:159]
	s_add_i32 m0, s58, 0x2000
	s_nop 0
	global_load_lds_dwordx4 v[228:229], off
	v_lshl_add_u64 v[228:229], s[54:55], 0, v[152:153]
	s_mov_b32 m0, s60
	s_nop 0
	global_load_lds_dwordx4 v[228:229], off
	s_mov_b32 m0, s61
	s_nop 0
	global_load_lds_dwordx4 v[230:231], off
	s_waitcnt vmcnt(8)
	s_waitcnt lgkmcnt(0)
	s_waitcnt lgkmcnt(0)
	s_setprio 1
	s_barrier
	v_mfma_f32_16x16x32_bf16 v[60:63], v[128:131], v[194:197], 0
	v_mfma_f32_16x16x32_bf16 v[56:59], v[136:139], v[194:197], 0
	v_mfma_f32_16x16x32_bf16 v[44:47], v[128:131], v[202:205], 0
	v_mfma_f32_16x16x32_bf16 v[40:43], v[136:139], v[202:205], 0
	v_mfma_f32_16x16x32_bf16 v[28:31], v[128:131], v[210:213], 0
	v_mfma_f32_16x16x32_bf16 v[24:27], v[136:139], v[210:213], 0
	v_mfma_f32_16x16x32_bf16 v[12:15], v[128:131], v[218:221], 0
	v_mfma_f32_16x16x32_bf16 v[8:11], v[136:139], v[218:221], 0
	v_mfma_f32_16x16x32_bf16 v[60:63], v[132:135], v[198:201], v[60:63]
	v_mfma_f32_16x16x32_bf16 v[56:59], v[140:143], v[198:201], v[56:59]
	v_mfma_f32_16x16x32_bf16 v[44:47], v[132:135], v[206:209], v[44:47]
	v_mfma_f32_16x16x32_bf16 v[40:43], v[140:143], v[206:209], v[40:43]
	v_mfma_f32_16x16x32_bf16 v[28:31], v[132:135], v[214:217], v[28:31]
	v_mfma_f32_16x16x32_bf16 v[24:27], v[140:143], v[214:217], v[24:27]
	v_mfma_f32_16x16x32_bf16 v[12:15], v[132:135], v[222:225], v[12:15]
	v_mfma_f32_16x16x32_bf16 v[8:11], v[140:143], v[222:225], v[8:11]
	s_setprio 0
	s_setprio 1
	v_mfma_f32_16x16x32_bf16 v[52:55], v[144:147], v[194:197], 0
	v_mfma_f32_16x16x32_bf16 v[48:51], v[176:179], v[194:197], 0
	v_mfma_f32_16x16x32_bf16 v[36:39], v[144:147], v[202:205], 0
	v_mfma_f32_16x16x32_bf16 v[32:35], v[176:179], v[202:205], 0
	v_mfma_f32_16x16x32_bf16 v[20:23], v[144:147], v[210:213], 0
	v_mfma_f32_16x16x32_bf16 v[16:19], v[176:179], v[210:213], 0
	v_mfma_f32_16x16x32_bf16 v[4:7], v[144:147], v[218:221], 0
	v_mfma_f32_16x16x32_bf16 v[0:3], v[176:179], v[218:221], 0
	v_mfma_f32_16x16x32_bf16 v[52:55], v[148:151], v[198:201], v[52:55]
	v_mfma_f32_16x16x32_bf16 v[48:51], v[180:183], v[198:201], v[48:51]
	v_mfma_f32_16x16x32_bf16 v[36:39], v[148:151], v[206:209], v[36:39]
	v_mfma_f32_16x16x32_bf16 v[32:35], v[180:183], v[206:209], v[32:35]
	v_mfma_f32_16x16x32_bf16 v[20:23], v[148:151], v[214:217], v[20:23]
	v_mfma_f32_16x16x32_bf16 v[16:19], v[180:183], v[214:217], v[16:19]
	v_mfma_f32_16x16x32_bf16 v[4:7], v[148:151], v[222:225], v[4:7]
	v_mfma_f32_16x16x32_bf16 v[0:3], v[180:183], v[222:225], v[0:3]
	s_barrier
	s_setprio 0
	s_branch .Lpeel_mid_p1
.LBB0_146:
	ds_read_b128 v[128:131], v188
	ds_read_b128 v[132:135], v188 offset:1024
	ds_read_b128 v[136:139], v188 offset:2048
	ds_read_b128 v[140:143], v188 offset:3072
	ds_read_b128 v[144:147], v189
	ds_read_b128 v[148:151], v189 offset:1024
	ds_read_b128 v[176:179], v189 offset:2048
	ds_read_b128 v[180:183], v189 offset:3072
	s_add_u32 s50, s48, 0x100
	s_addc_u32 s51, s49, 0
	s_cmp_eq_u32 s57, 28
	s_cselect_b32 s55, s21, s51
	s_cselect_b32 s54, s20, s50
	s_cselect_b32 s53, s23, s56
	s_cselect_b32 s52, s22, s27
	v_lshl_add_u64 v[184:185], s[48:49], 0, v[170:171]
	s_add_i32 m0, s60, 0xc000
	ds_read_b128 v[194:197], v190
	ds_read_b128 v[198:201], v190 offset:1024
	ds_read_b128 v[202:205], v190 offset:2048
	ds_read_b128 v[206:209], v190 offset:3072
	ds_read_b128 v[210:213], v190 offset:4096
	ds_read_b128 v[214:217], v190 offset:5120
	ds_read_b128 v[218:221], v190 offset:6144
	ds_read_b128 v[222:225], v190 offset:7168
	global_load_lds_dwordx4 v[184:185], off
	v_lshl_add_u64 v[184:185], s[48:49], 0, v[172:173]
	s_add_i32 m0, s60, 0xe000
	s_nop 0
	global_load_lds_dwordx4 v[184:185], off
	s_waitcnt vmcnt(8)
	s_waitcnt lgkmcnt(0)
	s_waitcnt lgkmcnt(0)
	s_setprio 1
	s_barrier
	v_mfma_f32_16x16x32_bf16 v[120:123], v[128:131], v[194:197], v[120:123]
	v_mfma_f32_16x16x32_bf16 v[124:127], v[136:139], v[194:197], v[124:127]
	v_mfma_f32_16x16x32_bf16 v[108:111], v[128:131], v[202:205], v[108:111]
	v_mfma_f32_16x16x32_bf16 v[104:107], v[136:139], v[202:205], v[104:107]
	v_mfma_f32_16x16x32_bf16 v[92:95], v[128:131], v[210:213], v[92:95]
	v_mfma_f32_16x16x32_bf16 v[88:91], v[136:139], v[210:213], v[88:91]
	v_mfma_f32_16x16x32_bf16 v[76:79], v[128:131], v[218:221], v[76:79]
	v_mfma_f32_16x16x32_bf16 v[72:75], v[136:139], v[218:221], v[72:75]
	v_mfma_f32_16x16x32_bf16 v[120:123], v[132:135], v[198:201], v[120:123]
	v_mfma_f32_16x16x32_bf16 v[124:127], v[140:143], v[198:201], v[124:127]
	v_mfma_f32_16x16x32_bf16 v[108:111], v[132:135], v[206:209], v[108:111]
	v_mfma_f32_16x16x32_bf16 v[104:107], v[140:143], v[206:209], v[104:107]
	v_mfma_f32_16x16x32_bf16 v[92:95], v[132:135], v[214:217], v[92:95]
	v_mfma_f32_16x16x32_bf16 v[88:91], v[140:143], v[214:217], v[88:91]
	v_mfma_f32_16x16x32_bf16 v[76:79], v[132:135], v[222:225], v[76:79]
	v_mfma_f32_16x16x32_bf16 v[72:75], v[140:143], v[222:225], v[72:75]
	s_setprio 0
	s_setprio 1
	v_mfma_f32_16x16x32_bf16 v[112:115], v[144:147], v[194:197], v[112:115]
	v_mfma_f32_16x16x32_bf16 v[116:119], v[176:179], v[194:197], v[116:119]
	v_mfma_f32_16x16x32_bf16 v[100:103], v[144:147], v[202:205], v[100:103]
	v_mfma_f32_16x16x32_bf16 v[96:99], v[176:179], v[202:205], v[96:99]
	v_mfma_f32_16x16x32_bf16 v[84:87], v[144:147], v[210:213], v[84:87]
	v_mfma_f32_16x16x32_bf16 v[80:83], v[176:179], v[210:213], v[80:83]
	v_mfma_f32_16x16x32_bf16 v[68:71], v[144:147], v[218:221], v[68:71]
	v_mfma_f32_16x16x32_bf16 v[64:67], v[176:179], v[218:221], v[64:67]
	v_mfma_f32_16x16x32_bf16 v[112:115], v[148:151], v[198:201], v[112:115]
	v_mfma_f32_16x16x32_bf16 v[116:119], v[180:183], v[198:201], v[116:119]
	v_mfma_f32_16x16x32_bf16 v[100:103], v[148:151], v[206:209], v[100:103]
	v_mfma_f32_16x16x32_bf16 v[96:99], v[180:183], v[206:209], v[96:99]
	v_mfma_f32_16x16x32_bf16 v[84:87], v[148:151], v[214:217], v[84:87]
	v_mfma_f32_16x16x32_bf16 v[80:83], v[180:183], v[214:217], v[80:83]
	v_mfma_f32_16x16x32_bf16 v[68:71], v[148:151], v[222:225], v[68:71]
	v_mfma_f32_16x16x32_bf16 v[64:67], v[180:183], v[222:225], v[64:67]
	s_barrier
	s_setprio 0
	s_add_i32 s48, s71, s3
	v_lshl_add_u64 v[184:185], s[52:53], 0, v[154:155]
	s_mov_b32 m0, s48
	ds_read_b128 v[194:197], v190 offset:16384
	ds_read_b128 v[198:201], v190 offset:17408
	ds_read_b128 v[202:205], v190 offset:18432
	ds_read_b128 v[206:209], v190 offset:19456
	ds_read_b128 v[210:213], v190 offset:20480
	ds_read_b128 v[214:217], v190 offset:21504
	ds_read_b128 v[218:221], v190 offset:22528
	ds_read_b128 v[222:225], v190 offset:23552
	global_load_lds_dwordx4 v[184:185], off
	s_add_i32 m0, s48, 0x2000
	s_add_u32 s48, s52, 0x80000
	v_lshl_add_u64 v[226:227], s[52:53], 0, v[158:159]
	s_addc_u32 s49, s53, 0
	s_add_i32 s58, s72, s3
	global_load_lds_dwordx4 v[226:227], off
	v_lshl_add_u64 v[228:229], s[48:49], 0, v[154:155]
	s_mov_b32 m0, s58
	v_lshl_add_u64 v[230:231], s[54:55], 0, v[156:157]
	global_load_lds_dwordx4 v[228:229], off
	v_lshl_add_u64 v[228:229], s[48:49], 0, v[158:159]
	s_add_i32 m0, s58, 0x2000
	s_nop 0
	global_load_lds_dwordx4 v[228:229], off
	v_lshl_add_u64 v[228:229], s[54:55], 0, v[152:153]
	s_mov_b32 m0, s60
	s_nop 0
	global_load_lds_dwordx4 v[228:229], off
	s_mov_b32 m0, s61
	s_nop 0
	global_load_lds_dwordx4 v[230:231], off
	s_waitcnt vmcnt(8)
	s_waitcnt lgkmcnt(0)
	s_waitcnt lgkmcnt(0)
	s_setprio 1
	s_barrier
	v_mfma_f32_16x16x32_bf16 v[60:63], v[128:131], v[194:197], v[60:63]
	v_mfma_f32_16x16x32_bf16 v[56:59], v[136:139], v[194:197], v[56:59]
	v_mfma_f32_16x16x32_bf16 v[44:47], v[128:131], v[202:205], v[44:47]
	v_mfma_f32_16x16x32_bf16 v[40:43], v[136:139], v[202:205], v[40:43]
	v_mfma_f32_16x16x32_bf16 v[28:31], v[128:131], v[210:213], v[28:31]
	v_mfma_f32_16x16x32_bf16 v[24:27], v[136:139], v[210:213], v[24:27]
	v_mfma_f32_16x16x32_bf16 v[12:15], v[128:131], v[218:221], v[12:15]
	v_mfma_f32_16x16x32_bf16 v[8:11], v[136:139], v[218:221], v[8:11]
	v_mfma_f32_16x16x32_bf16 v[60:63], v[132:135], v[198:201], v[60:63]
	v_mfma_f32_16x16x32_bf16 v[56:59], v[140:143], v[198:201], v[56:59]
	v_mfma_f32_16x16x32_bf16 v[44:47], v[132:135], v[206:209], v[44:47]
	v_mfma_f32_16x16x32_bf16 v[40:43], v[140:143], v[206:209], v[40:43]
	v_mfma_f32_16x16x32_bf16 v[28:31], v[132:135], v[214:217], v[28:31]
	v_mfma_f32_16x16x32_bf16 v[24:27], v[140:143], v[214:217], v[24:27]
	v_mfma_f32_16x16x32_bf16 v[12:15], v[132:135], v[222:225], v[12:15]
	v_mfma_f32_16x16x32_bf16 v[8:11], v[140:143], v[222:225], v[8:11]
	s_setprio 0
	s_setprio 1
	v_mfma_f32_16x16x32_bf16 v[52:55], v[144:147], v[194:197], v[52:55]
	v_mfma_f32_16x16x32_bf16 v[48:51], v[176:179], v[194:197], v[48:51]
	v_mfma_f32_16x16x32_bf16 v[36:39], v[144:147], v[202:205], v[36:39]
	v_mfma_f32_16x16x32_bf16 v[32:35], v[176:179], v[202:205], v[32:35]
	v_mfma_f32_16x16x32_bf16 v[20:23], v[144:147], v[210:213], v[20:23]
	v_mfma_f32_16x16x32_bf16 v[16:19], v[176:179], v[210:213], v[16:19]
	v_mfma_f32_16x16x32_bf16 v[4:7], v[144:147], v[218:221], v[4:7]
	v_mfma_f32_16x16x32_bf16 v[0:3], v[176:179], v[218:221], v[0:3]
	v_mfma_f32_16x16x32_bf16 v[52:55], v[148:151], v[198:201], v[52:55]
	v_mfma_f32_16x16x32_bf16 v[48:51], v[180:183], v[198:201], v[48:51]
	v_mfma_f32_16x16x32_bf16 v[36:39], v[148:151], v[206:209], v[36:39]
	v_mfma_f32_16x16x32_bf16 v[32:35], v[180:183], v[206:209], v[32:35]
	v_mfma_f32_16x16x32_bf16 v[20:23], v[148:151], v[214:217], v[20:23]
	v_mfma_f32_16x16x32_bf16 v[16:19], v[180:183], v[214:217], v[16:19]
	v_mfma_f32_16x16x32_bf16 v[4:7], v[148:151], v[222:225], v[4:7]
	v_mfma_f32_16x16x32_bf16 v[0:3], v[180:183], v[222:225], v[0:3]
	s_barrier
	s_setprio 0
.Lpeel_mid_p1:
	s_add_i32 s58, 0, 0x18000
	s_add_i32 s59, 0, 0x1c000
	v_add_u32_e32 v140, s58, v186
	v_add_u32_e32 v160, s59, v186
	ds_read_b128 v[128:131], v140
	ds_read_b128 v[132:135], v140 offset:1024
	ds_read_b128 v[136:139], v140 offset:2048
	ds_read_b128 v[140:143], v140 offset:3072
	ds_read_b128 v[144:147], v160
	ds_read_b128 v[148:151], v160 offset:1024
	ds_read_b128 v[176:179], v160 offset:2048
	ds_read_b128 v[180:183], v160 offset:3072
	s_add_u32 s48, s54, 0xa0000
	s_addc_u32 s49, s55, 0
	s_mov_b32 m0, s62
	v_lshl_add_u64 v[232:233], s[48:49], 0, v[152:153]
	ds_read_b128 v[194:197], v190 offset:32768
	ds_read_b128 v[198:201], v190 offset:33792
	ds_read_b128 v[202:205], v190 offset:34816
	ds_read_b128 v[206:209], v190 offset:35840
	ds_read_b128 v[210:213], v190 offset:36864
	ds_read_b128 v[214:217], v190 offset:37888
	ds_read_b128 v[218:221], v190 offset:38912
	ds_read_b128 v[222:225], v190 offset:39936
	global_load_lds_dwordx4 v[232:233], off
	v_lshl_add_u64 v[232:233], s[48:49], 0, v[156:157]
	s_mov_b32 m0, s63
	s_nop 0
	global_load_lds_dwordx4 v[232:233], off
	s_waitcnt vmcnt(8)
	s_waitcnt lgkmcnt(0)
	s_waitcnt lgkmcnt(0)
	s_setprio 1
	s_barrier
	v_mfma_f32_16x16x32_bf16 v[120:123], v[128:131], v[194:197], v[120:123]
	v_mfma_f32_16x16x32_bf16 v[124:127], v[136:139], v[194:197], v[124:127]
	v_mfma_f32_16x16x32_bf16 v[108:111], v[128:131], v[202:205], v[108:111]
	v_mfma_f32_16x16x32_bf16 v[104:107], v[136:139], v[202:205], v[104:107]
	v_mfma_f32_16x16x32_bf16 v[92:95], v[128:131], v[210:213], v[92:95]
	v_mfma_f32_16x16x32_bf16 v[88:91], v[136:139], v[210:213], v[88:91]
	v_mfma_f32_16x16x32_bf16 v[76:79], v[128:131], v[218:221], v[76:79]
	v_mfma_f32_16x16x32_bf16 v[72:75], v[136:139], v[218:221], v[72:75]
	v_mfma_f32_16x16x32_bf16 v[120:123], v[132:135], v[198:201], v[120:123]
	v_mfma_f32_16x16x32_bf16 v[124:127], v[140:143], v[198:201], v[124:127]
	v_mfma_f32_16x16x32_bf16 v[108:111], v[132:135], v[206:209], v[108:111]
	v_mfma_f32_16x16x32_bf16 v[104:107], v[140:143], v[206:209], v[104:107]
	v_mfma_f32_16x16x32_bf16 v[92:95], v[132:135], v[214:217], v[92:95]
	v_mfma_f32_16x16x32_bf16 v[88:91], v[140:143], v[214:217], v[88:91]
	v_mfma_f32_16x16x32_bf16 v[76:79], v[132:135], v[222:225], v[76:79]
	v_mfma_f32_16x16x32_bf16 v[72:75], v[140:143], v[222:225], v[72:75]
	s_setprio 0
	s_setprio 1
	v_mfma_f32_16x16x32_bf16 v[112:115], v[144:147], v[194:197], v[112:115]
	v_mfma_f32_16x16x32_bf16 v[116:119], v[176:179], v[194:197], v[116:119]
	v_mfma_f32_16x16x32_bf16 v[100:103], v[144:147], v[202:205], v[100:103]
	v_mfma_f32_16x16x32_bf16 v[96:99], v[176:179], v[202:205], v[96:99]
	v_mfma_f32_16x16x32_bf16 v[84:87], v[144:147], v[210:213], v[84:87]
	v_mfma_f32_16x16x32_bf16 v[80:83], v[176:179], v[210:213], v[80:83]
	v_mfma_f32_16x16x32_bf16 v[68:71], v[144:147], v[218:221], v[68:71]
	v_mfma_f32_16x16x32_bf16 v[64:67], v[176:179], v[218:221], v[64:67]
	v_mfma_f32_16x16x32_bf16 v[112:115], v[148:151], v[198:201], v[112:115]
	v_mfma_f32_16x16x32_bf16 v[116:119], v[180:183], v[198:201], v[116:119]
	v_mfma_f32_16x16x32_bf16 v[100:103], v[148:151], v[206:209], v[100:103]
	v_mfma_f32_16x16x32_bf16 v[96:99], v[180:183], v[206:209], v[96:99]
	v_mfma_f32_16x16x32_bf16 v[84:87], v[148:151], v[214:217], v[84:87]
	v_mfma_f32_16x16x32_bf16 v[80:83], v[180:183], v[214:217], v[80:83]
	v_mfma_f32_16x16x32_bf16 v[68:71], v[148:151], v[222:225], v[68:71]
	v_mfma_f32_16x16x32_bf16 v[64:67], v[180:183], v[222:225], v[64:67]
	s_barrier
	s_setprio 0
	s_add_i32 s48, s58, s3
	v_lshl_add_u64 v[184:185], v[184:185], 0, s[14:15]
	s_mov_b32 m0, s48
	ds_read_b128 v[194:197], v190 offset:49152
	ds_read_b128 v[198:201], v190 offset:50176
	ds_read_b128 v[202:205], v190 offset:51200
	ds_read_b128 v[206:209], v190 offset:52224
	ds_read_b128 v[210:213], v190 offset:53248
	ds_read_b128 v[214:217], v190 offset:54272
	ds_read_b128 v[218:221], v190 offset:55296
	ds_read_b128 v[222:225], v190 offset:56320
	global_load_lds_dwordx4 v[184:185], off
	s_add_i32 m0, s48, 0x2000
	s_add_u32 s48, s52, 0x80080
	v_lshl_add_u64 v[184:185], v[226:227], 0, s[14:15]
	s_addc_u32 s49, s53, 0
	s_add_i32 s52, s59, s3
	global_load_lds_dwordx4 v[184:185], off
	v_lshl_add_u64 v[184:185], s[48:49], 0, v[154:155]
	s_mov_b32 m0, s52
	s_nop 0
	global_load_lds_dwordx4 v[184:185], off
	v_lshl_add_u64 v[184:185], s[48:49], 0, v[158:159]
	s_add_i32 m0, s52, 0x2000
	s_nop 0
	global_load_lds_dwordx4 v[184:185], off
	v_lshl_add_u64 v[184:185], v[228:229], 0, s[14:15]
	s_mov_b32 m0, s66
	s_nop 0
	global_load_lds_dwordx4 v[184:185], off
	v_lshl_add_u64 v[184:185], v[230:231], 0, s[14:15]
	s_mov_b32 m0, s67
	s_nop 0
	global_load_lds_dwordx4 v[184:185], off
	s_waitcnt vmcnt(8)
	s_waitcnt lgkmcnt(0)
	s_waitcnt lgkmcnt(0)
	s_setprio 1
	s_barrier
	v_mfma_f32_16x16x32_bf16 v[60:63], v[128:131], v[194:197], v[60:63]
	v_mfma_f32_16x16x32_bf16 v[56:59], v[136:139], v[194:197], v[56:59]
	v_mfma_f32_16x16x32_bf16 v[44:47], v[128:131], v[202:205], v[44:47]
	v_mfma_f32_16x16x32_bf16 v[40:43], v[136:139], v[202:205], v[40:43]
	v_mfma_f32_16x16x32_bf16 v[28:31], v[128:131], v[210:213], v[28:31]
	v_mfma_f32_16x16x32_bf16 v[24:27], v[136:139], v[210:213], v[24:27]
	v_mfma_f32_16x16x32_bf16 v[12:15], v[128:131], v[218:221], v[12:15]
	v_mfma_f32_16x16x32_bf16 v[8:11], v[136:139], v[218:221], v[8:11]
	v_mfma_f32_16x16x32_bf16 v[60:63], v[132:135], v[198:201], v[60:63]
	v_mfma_f32_16x16x32_bf16 v[56:59], v[140:143], v[198:201], v[56:59]
	v_mfma_f32_16x16x32_bf16 v[44:47], v[132:135], v[206:209], v[44:47]
	v_mfma_f32_16x16x32_bf16 v[40:43], v[140:143], v[206:209], v[40:43]
	v_mfma_f32_16x16x32_bf16 v[28:31], v[132:135], v[214:217], v[28:31]
	v_mfma_f32_16x16x32_bf16 v[24:27], v[140:143], v[214:217], v[24:27]
	v_mfma_f32_16x16x32_bf16 v[12:15], v[132:135], v[222:225], v[12:15]
	v_mfma_f32_16x16x32_bf16 v[8:11], v[140:143], v[222:225], v[8:11]
	s_setprio 0
	s_setprio 1
	v_mfma_f32_16x16x32_bf16 v[52:55], v[144:147], v[194:197], v[52:55]
	v_mfma_f32_16x16x32_bf16 v[48:51], v[176:179], v[194:197], v[48:51]
	v_mfma_f32_16x16x32_bf16 v[36:39], v[144:147], v[202:205], v[36:39]
	v_mfma_f32_16x16x32_bf16 v[32:35], v[176:179], v[202:205], v[32:35]
	v_mfma_f32_16x16x32_bf16 v[20:23], v[144:147], v[210:213], v[20:23]
	v_mfma_f32_16x16x32_bf16 v[16:19], v[176:179], v[210:213], v[16:19]
	v_mfma_f32_16x16x32_bf16 v[4:7], v[144:147], v[218:221], v[4:7]
	v_mfma_f32_16x16x32_bf16 v[0:3], v[176:179], v[218:221], v[0:3]
	v_mfma_f32_16x16x32_bf16 v[52:55], v[148:151], v[198:201], v[52:55]
	v_mfma_f32_16x16x32_bf16 v[48:51], v[180:183], v[198:201], v[48:51]
	v_mfma_f32_16x16x32_bf16 v[36:39], v[148:151], v[206:209], v[36:39]
	v_mfma_f32_16x16x32_bf16 v[32:35], v[180:183], v[206:209], v[32:35]
	v_mfma_f32_16x16x32_bf16 v[20:23], v[148:151], v[214:217], v[20:23]
	v_mfma_f32_16x16x32_bf16 v[16:19], v[180:183], v[214:217], v[16:19]
	v_mfma_f32_16x16x32_bf16 v[4:7], v[148:151], v[222:225], v[4:7]
	v_mfma_f32_16x16x32_bf16 v[0:3], v[180:183], v[222:225], v[0:3]
	s_barrier
	s_setprio 0
	s_add_i32 s57, s57, 2
	s_add_u32 s27, s27, 0x100
	s_addc_u32 s56, s56, 0
	s_cmp_gt_u32 s57, 29
	s_mov_b64 s[48:49], s[50:51]
	s_cbranch_scc0 .LBB0_146
	s_and_b64 vcc, exec, s[18:19]
	s_cbranch_vccz .LBB0_149
	s_barrier

.LBB0_250:
	ds_read_b128 v[148:151], v142
	ds_read_b128 v[152:155], v142 offset:1024
	ds_read_b128 v[156:159], v142 offset:2048
	ds_read_b128 v[160:163], v142 offset:3072
	ds_read_b128 v[164:167], v143
	ds_read_b128 v[168:171], v143 offset:1024
	ds_read_b128 v[176:179], v143 offset:2048
	ds_read_b128 v[180:183], v143 offset:3072
	s_add_i32 s20, s18, 0xf4f60080
	s_cmp_lg_u32 s52, 28
	s_cselect_b32 s20, s20, 0
	s_add_u32 s22, s2, s20
	s_addc_u32 s23, s3, 0
	s_add_u32 s20, s12, s20
	s_addc_u32 s21, s13, 0
	s_mov_b32 m0, s53
	v_lshl_add_u64 v[172:173], v[138:139], 0, s[18:19]
	ds_read_b128 v[188:191], v144
	ds_read_b128 v[192:195], v144 offset:1024
	ds_read_b128 v[196:199], v144 offset:2048
	ds_read_b128 v[200:203], v144 offset:3072
	ds_read_b128 v[204:207], v144 offset:4096
	ds_read_b128 v[208:211], v144 offset:5120
	ds_read_b128 v[212:215], v144 offset:6144
	ds_read_b128 v[216:219], v144 offset:7168
	global_load_lds_dwordx4 v[172:173], off
	v_lshl_add_u64 v[172:173], v[140:141], 0, s[18:19]
	s_mov_b32 m0, s54
	s_nop 0
	global_load_lds_dwordx4 v[172:173], off
	s_waitcnt vmcnt(8)
	s_waitcnt lgkmcnt(0)
	s_waitcnt lgkmcnt(0)
	s_setprio 1
	s_barrier
	v_mfma_f32_16x16x32_bf16 v[124:127], v[148:151], v[188:191], v[124:127]
	v_mfma_f32_16x16x32_bf16 v[120:123], v[156:159], v[188:191], v[120:123]
	v_mfma_f32_16x16x32_bf16 v[116:119], v[148:151], v[196:199], v[116:119]
	v_mfma_f32_16x16x32_bf16 v[112:115], v[156:159], v[196:199], v[112:115]
	v_mfma_f32_16x16x32_bf16 v[100:103], v[148:151], v[204:207], v[100:103]
	v_mfma_f32_16x16x32_bf16 v[96:99], v[156:159], v[204:207], v[96:99]
	v_mfma_f32_16x16x32_bf16 v[84:87], v[148:151], v[212:215], v[84:87]
	v_mfma_f32_16x16x32_bf16 v[80:83], v[156:159], v[212:215], v[80:83]
	v_mfma_f32_16x16x32_bf16 v[124:127], v[152:155], v[192:195], v[124:127]
	v_mfma_f32_16x16x32_bf16 v[120:123], v[160:163], v[192:195], v[120:123]
	v_mfma_f32_16x16x32_bf16 v[116:119], v[152:155], v[200:203], v[116:119]
	v_mfma_f32_16x16x32_bf16 v[112:115], v[160:163], v[200:203], v[112:115]
	v_mfma_f32_16x16x32_bf16 v[100:103], v[152:155], v[208:211], v[100:103]
	v_mfma_f32_16x16x32_bf16 v[96:99], v[160:163], v[208:211], v[96:99]
	v_mfma_f32_16x16x32_bf16 v[84:87], v[152:155], v[216:219], v[84:87]
	v_mfma_f32_16x16x32_bf16 v[80:83], v[160:163], v[216:219], v[80:83]
	s_setprio 0
	s_setprio 1
	v_mfma_f32_16x16x32_bf16 v[108:111], v[164:167], v[188:191], v[108:111]
	v_mfma_f32_16x16x32_bf16 v[104:107], v[176:179], v[188:191], v[104:107]
	v_mfma_f32_16x16x32_bf16 v[92:95], v[164:167], v[196:199], v[92:95]
	v_mfma_f32_16x16x32_bf16 v[88:91], v[176:179], v[196:199], v[88:91]
	v_mfma_f32_16x16x32_bf16 v[76:79], v[164:167], v[204:207], v[76:79]
	v_mfma_f32_16x16x32_bf16 v[72:75], v[176:179], v[204:207], v[72:75]
	v_mfma_f32_16x16x32_bf16 v[68:71], v[164:167], v[212:215], v[68:71]
	v_mfma_f32_16x16x32_bf16 v[64:67], v[176:179], v[212:215], v[64:67]
	v_mfma_f32_16x16x32_bf16 v[108:111], v[168:171], v[192:195], v[108:111]
	v_mfma_f32_16x16x32_bf16 v[104:107], v[180:183], v[192:195], v[104:107]
	v_mfma_f32_16x16x32_bf16 v[92:95], v[168:171], v[200:203], v[92:95]
	v_mfma_f32_16x16x32_bf16 v[88:91], v[180:183], v[200:203], v[88:91]
	v_mfma_f32_16x16x32_bf16 v[76:79], v[168:171], v[208:211], v[76:79]
	v_mfma_f32_16x16x32_bf16 v[72:75], v[180:183], v[208:211], v[72:75]
	v_mfma_f32_16x16x32_bf16 v[68:71], v[168:171], v[216:219], v[68:71]
	v_mfma_f32_16x16x32_bf16 v[64:67], v[180:183], v[216:219], v[64:67]
	s_barrier
	s_setprio 0
	s_mov_b32 m0, s55
	v_lshl_add_u64 v[172:173], s[20:21], 0, v[132:133]
	s_add_u32 s64, s20, 0x80000
	ds_read_b128 v[188:191], v144 offset:16384
	ds_read_b128 v[192:195], v144 offset:17408
	ds_read_b128 v[196:199], v144 offset:18432
	ds_read_b128 v[200:203], v144 offset:19456
	ds_read_b128 v[204:207], v144 offset:20480
	ds_read_b128 v[208:211], v144 offset:21504
	ds_read_b128 v[212:215], v144 offset:22528
	ds_read_b128 v[216:219], v144 offset:23552
	global_load_lds_dwordx4 v[172:173], off
	v_lshl_add_u64 v[184:185], s[20:21], 0, v[128:129]
	s_mov_b32 m0, s56
	s_addc_u32 s65, s21, 0
	global_load_lds_dwordx4 v[184:185], off
	v_lshl_add_u64 v[220:221], s[64:65], 0, v[132:133]
	s_mov_b32 m0, s57
	v_lshl_add_u64 v[222:223], s[22:23], 0, v[130:131]
	global_load_lds_dwordx4 v[220:221], off
	v_lshl_add_u64 v[220:221], s[64:65], 0, v[128:129]
	s_mov_b32 m0, s58
	s_nop 0
	global_load_lds_dwordx4 v[220:221], off
	v_lshl_add_u64 v[220:221], s[22:23], 0, v[134:135]
	s_mov_b32 m0, s1
	s_nop 0
	global_load_lds_dwordx4 v[220:221], off
	s_mov_b32 m0, s26
	s_nop 0
	global_load_lds_dwordx4 v[222:223], off
	s_waitcnt vmcnt(8)
	s_waitcnt lgkmcnt(0)
	s_waitcnt lgkmcnt(0)
	s_setprio 1
	s_barrier
	v_mfma_f32_16x16x32_bf16 v[60:63], v[148:151], v[188:191], v[60:63]
	v_mfma_f32_16x16x32_bf16 v[56:59], v[156:159], v[188:191], v[56:59]
	v_mfma_f32_16x16x32_bf16 v[52:55], v[148:151], v[196:199], v[52:55]
	v_mfma_f32_16x16x32_bf16 v[48:51], v[156:159], v[196:199], v[48:51]
	v_mfma_f32_16x16x32_bf16 v[36:39], v[148:151], v[204:207], v[36:39]
	v_mfma_f32_16x16x32_bf16 v[32:35], v[156:159], v[204:207], v[32:35]
	v_mfma_f32_16x16x32_bf16 v[20:23], v[148:151], v[212:215], v[20:23]
	v_mfma_f32_16x16x32_bf16 v[16:19], v[156:159], v[212:215], v[16:19]
	v_mfma_f32_16x16x32_bf16 v[60:63], v[152:155], v[192:195], v[60:63]
	v_mfma_f32_16x16x32_bf16 v[56:59], v[160:163], v[192:195], v[56:59]
	v_mfma_f32_16x16x32_bf16 v[52:55], v[152:155], v[200:203], v[52:55]
	v_mfma_f32_16x16x32_bf16 v[48:51], v[160:163], v[200:203], v[48:51]
	v_mfma_f32_16x16x32_bf16 v[36:39], v[152:155], v[208:211], v[36:39]
	v_mfma_f32_16x16x32_bf16 v[32:35], v[160:163], v[208:211], v[32:35]
	v_mfma_f32_16x16x32_bf16 v[20:23], v[152:155], v[216:219], v[20:23]
	v_mfma_f32_16x16x32_bf16 v[16:19], v[160:163], v[216:219], v[16:19]
	s_setprio 0
	s_setprio 1
	v_mfma_f32_16x16x32_bf16 v[44:47], v[164:167], v[188:191], v[44:47]
	v_mfma_f32_16x16x32_bf16 v[40:43], v[176:179], v[188:191], v[40:43]
	v_mfma_f32_16x16x32_bf16 v[28:31], v[164:167], v[196:199], v[28:31]
	v_mfma_f32_16x16x32_bf16 v[24:27], v[176:179], v[196:199], v[24:27]
	v_mfma_f32_16x16x32_bf16 v[12:15], v[164:167], v[204:207], v[12:15]
	v_mfma_f32_16x16x32_bf16 v[8:11], v[176:179], v[204:207], v[8:11]
	v_mfma_f32_16x16x32_bf16 v[4:7], v[164:167], v[212:215], v[4:7]
	v_mfma_f32_16x16x32_bf16 v[0:3], v[176:179], v[212:215], v[0:3]
	v_mfma_f32_16x16x32_bf16 v[44:47], v[168:171], v[192:195], v[44:47]
	v_mfma_f32_16x16x32_bf16 v[40:43], v[180:183], v[192:195], v[40:43]
	v_mfma_f32_16x16x32_bf16 v[28:31], v[168:171], v[200:203], v[28:31]
	v_mfma_f32_16x16x32_bf16 v[24:27], v[180:183], v[200:203], v[24:27]
	v_mfma_f32_16x16x32_bf16 v[12:15], v[168:171], v[208:211], v[12:15]
	v_mfma_f32_16x16x32_bf16 v[8:11], v[180:183], v[208:211], v[8:11]
	v_mfma_f32_16x16x32_bf16 v[4:7], v[168:171], v[216:219], v[4:7]
	v_mfma_f32_16x16x32_bf16 v[0:3], v[180:183], v[216:219], v[0:3]
	s_barrier
	s_setprio 0
	ds_read_b128 v[148:151], v145
	ds_read_b128 v[152:155], v145 offset:1024
	ds_read_b128 v[156:159], v145 offset:2048
	ds_read_b128 v[160:163], v145 offset:3072
	ds_read_b128 v[164:167], v146
	ds_read_b128 v[168:171], v146 offset:1024
	ds_read_b128 v[176:179], v146 offset:2048
	ds_read_b128 v[180:183], v146 offset:3072
	s_add_u32 s22, s22, 0xa0000
	s_addc_u32 s23, s23, 0
	s_mov_b32 m0, s27
	v_lshl_add_u64 v[224:225], s[22:23], 0, v[134:135]
	ds_read_b128 v[188:191], v144 offset:32768
	ds_read_b128 v[192:195], v144 offset:33792
	ds_read_b128 v[196:199], v144 offset:34816
	ds_read_b128 v[200:203], v144 offset:35840
	ds_read_b128 v[204:207], v144 offset:36864
	ds_read_b128 v[208:211], v144 offset:37888
	ds_read_b128 v[212:215], v144 offset:38912
	ds_read_b128 v[216:219], v144 offset:39936
	global_load_lds_dwordx4 v[224:225], off
	v_lshl_add_u64 v[224:225], s[22:23], 0, v[130:131]
	s_mov_b32 m0, s48
	s_nop 0
	global_load_lds_dwordx4 v[224:225], off
	s_waitcnt vmcnt(8)
	s_waitcnt lgkmcnt(0)
	s_waitcnt lgkmcnt(0)
	s_setprio 1
	s_barrier
	v_mfma_f32_16x16x32_bf16 v[124:127], v[148:151], v[188:191], v[124:127]
	v_mfma_f32_16x16x32_bf16 v[120:123], v[156:159], v[188:191], v[120:123]
	v_mfma_f32_16x16x32_bf16 v[116:119], v[148:151], v[196:199], v[116:119]
	v_mfma_f32_16x16x32_bf16 v[112:115], v[156:159], v[196:199], v[112:115]
	v_mfma_f32_16x16x32_bf16 v[100:103], v[148:151], v[204:207], v[100:103]
	v_mfma_f32_16x16x32_bf16 v[96:99], v[156:159], v[204:207], v[96:99]
	v_mfma_f32_16x16x32_bf16 v[84:87], v[148:151], v[212:215], v[84:87]
	v_mfma_f32_16x16x32_bf16 v[80:83], v[156:159], v[212:215], v[80:83]
	v_mfma_f32_16x16x32_bf16 v[124:127], v[152:155], v[192:195], v[124:127]
	v_mfma_f32_16x16x32_bf16 v[120:123], v[160:163], v[192:195], v[120:123]
	v_mfma_f32_16x16x32_bf16 v[116:119], v[152:155], v[200:203], v[116:119]
	v_mfma_f32_16x16x32_bf16 v[112:115], v[160:163], v[200:203], v[112:115]
	v_mfma_f32_16x16x32_bf16 v[100:103], v[152:155], v[208:211], v[100:103]
	v_mfma_f32_16x16x32_bf16 v[96:99], v[160:163], v[208:211], v[96:99]
	v_mfma_f32_16x16x32_bf16 v[84:87], v[152:155], v[216:219], v[84:87]
	v_mfma_f32_16x16x32_bf16 v[80:83], v[160:163], v[216:219], v[80:83]
	s_setprio 0
	s_setprio 1
	v_mfma_f32_16x16x32_bf16 v[108:111], v[164:167], v[188:191], v[108:111]
	v_mfma_f32_16x16x32_bf16 v[104:107], v[176:179], v[188:191], v[104:107]
	v_mfma_f32_16x16x32_bf16 v[92:95], v[164:167], v[196:199], v[92:95]
	v_mfma_f32_16x16x32_bf16 v[88:91], v[176:179], v[196:199], v[88:91]
	v_mfma_f32_16x16x32_bf16 v[76:79], v[164:167], v[204:207], v[76:79]
	v_mfma_f32_16x16x32_bf16 v[72:75], v[176:179], v[204:207], v[72:75]
	v_mfma_f32_16x16x32_bf16 v[68:71], v[164:167], v[212:215], v[68:71]
	v_mfma_f32_16x16x32_bf16 v[64:67], v[176:179], v[212:215], v[64:67]
	v_mfma_f32_16x16x32_bf16 v[108:111], v[168:171], v[192:195], v[108:111]
	v_mfma_f32_16x16x32_bf16 v[104:107], v[180:183], v[192:195], v[104:107]
	v_mfma_f32_16x16x32_bf16 v[92:95], v[168:171], v[200:203], v[92:95]
	v_mfma_f32_16x16x32_bf16 v[88:91], v[180:183], v[200:203], v[88:91]
	v_mfma_f32_16x16x32_bf16 v[76:79], v[168:171], v[208:211], v[76:79]
	v_mfma_f32_16x16x32_bf16 v[72:75], v[180:183], v[208:211], v[72:75]
	v_mfma_f32_16x16x32_bf16 v[68:71], v[168:171], v[216:219], v[68:71]
	v_mfma_f32_16x16x32_bf16 v[64:67], v[180:183], v[216:219], v[64:67]
	s_barrier
	s_setprio 0
	s_mov_b32 m0, s59
	v_lshl_add_u64 v[172:173], v[172:173], 0, s[14:15]
	s_add_u32 s20, s20, 0x80080
	ds_read_b128 v[188:191], v144 offset:49152
	ds_read_b128 v[192:195], v144 offset:50176
	ds_read_b128 v[196:199], v144 offset:51200
	ds_read_b128 v[200:203], v144 offset:52224
	ds_read_b128 v[204:207], v144 offset:53248
	ds_read_b128 v[208:211], v144 offset:54272
	ds_read_b128 v[212:215], v144 offset:55296
	ds_read_b128 v[216:219], v144 offset:56320
	global_load_lds_dwordx4 v[172:173], off
	v_lshl_add_u64 v[172:173], v[184:185], 0, s[14:15]
	s_mov_b32 m0, s60
	s_addc_u32 s21, s21, 0
	global_load_lds_dwordx4 v[172:173], off
	v_lshl_add_u64 v[172:173], s[20:21], 0, v[132:133]
	s_mov_b32 m0, s61
	s_nop 0
	global_load_lds_dwordx4 v[172:173], off
	v_lshl_add_u64 v[172:173], s[20:21], 0, v[128:129]
	s_mov_b32 m0, s62
	s_nop 0
	global_load_lds_dwordx4 v[172:173], off
	v_lshl_add_u64 v[172:173], v[220:221], 0, s[14:15]
	s_mov_b32 m0, s50
	s_nop 0
	global_load_lds_dwordx4 v[172:173], off
	v_lshl_add_u64 v[172:173], v[222:223], 0, s[14:15]
	s_mov_b32 m0, s51
	s_nop 0
	global_load_lds_dwordx4 v[172:173], off
	s_waitcnt vmcnt(8)
	s_waitcnt lgkmcnt(0)
	s_waitcnt lgkmcnt(0)
	s_setprio 1
	s_barrier
	v_mfma_f32_16x16x32_bf16 v[60:63], v[148:151], v[188:191], v[60:63]
	v_mfma_f32_16x16x32_bf16 v[56:59], v[156:159], v[188:191], v[56:59]
	v_mfma_f32_16x16x32_bf16 v[52:55], v[148:151], v[196:199], v[52:55]
	v_mfma_f32_16x16x32_bf16 v[48:51], v[156:159], v[196:199], v[48:51]
	v_mfma_f32_16x16x32_bf16 v[36:39], v[148:151], v[204:207], v[36:39]
	v_mfma_f32_16x16x32_bf16 v[32:35], v[156:159], v[204:207], v[32:35]
	v_mfma_f32_16x16x32_bf16 v[20:23], v[148:151], v[212:215], v[20:23]
	v_mfma_f32_16x16x32_bf16 v[16:19], v[156:159], v[212:215], v[16:19]
	v_mfma_f32_16x16x32_bf16 v[60:63], v[152:155], v[192:195], v[60:63]
	v_mfma_f32_16x16x32_bf16 v[56:59], v[160:163], v[192:195], v[56:59]
	v_mfma_f32_16x16x32_bf16 v[52:55], v[152:155], v[200:203], v[52:55]
	v_mfma_f32_16x16x32_bf16 v[48:51], v[160:163], v[200:203], v[48:51]
	v_mfma_f32_16x16x32_bf16 v[36:39], v[152:155], v[208:211], v[36:39]
	v_mfma_f32_16x16x32_bf16 v[32:35], v[160:163], v[208:211], v[32:35]
	v_mfma_f32_16x16x32_bf16 v[20:23], v[152:155], v[216:219], v[20:23]
	v_mfma_f32_16x16x32_bf16 v[16:19], v[160:163], v[216:219], v[16:19]
	s_setprio 0
	s_setprio 1
	v_mfma_f32_16x16x32_bf16 v[44:47], v[164:167], v[188:191], v[44:47]
	v_mfma_f32_16x16x32_bf16 v[40:43], v[176:179], v[188:191], v[40:43]
	v_mfma_f32_16x16x32_bf16 v[28:31], v[164:167], v[196:199], v[28:31]
	v_mfma_f32_16x16x32_bf16 v[24:27], v[176:179], v[196:199], v[24:27]
	v_mfma_f32_16x16x32_bf16 v[12:15], v[164:167], v[204:207], v[12:15]
	v_mfma_f32_16x16x32_bf16 v[8:11], v[176:179], v[204:207], v[8:11]
	v_mfma_f32_16x16x32_bf16 v[4:7], v[164:167], v[212:215], v[4:7]
	v_mfma_f32_16x16x32_bf16 v[0:3], v[176:179], v[212:215], v[0:3]
	v_mfma_f32_16x16x32_bf16 v[44:47], v[168:171], v[192:195], v[44:47]
	v_mfma_f32_16x16x32_bf16 v[40:43], v[180:183], v[192:195], v[40:43]
	v_mfma_f32_16x16x32_bf16 v[28:31], v[168:171], v[200:203], v[28:31]
	v_mfma_f32_16x16x32_bf16 v[24:27], v[180:183], v[200:203], v[24:27]
	v_mfma_f32_16x16x32_bf16 v[12:15], v[168:171], v[208:211], v[12:15]
	v_mfma_f32_16x16x32_bf16 v[8:11], v[180:183], v[208:211], v[8:11]
	v_mfma_f32_16x16x32_bf16 v[4:7], v[168:171], v[216:219], v[4:7]
	v_mfma_f32_16x16x32_bf16 v[0:3], v[180:183], v[216:219], v[0:3]
	s_barrier
	s_setprio 0
	s_add_i32 s52, s52, 2
	s_add_u32 s18, s18, 0x100
	s_addc_u32 s19, s19, 0
	s_cmp_gt_u32 s52, 29
	s_cbranch_scc0 .LBB0_250
	s_cmpk_lt_u32 s24, 0x100
	s_cbranch_scc0 .LBB0_253
	s_barrier

.LBB0_596:
	s_lshl_b32 s98, s56, 3
	s_add_i32 s98, s98, s2
	s_mul_i32 s98, s98, 3
	v_lshl_add_u32 v164, s56, 8, v172
	s_cmp_eq_u32 s87, 3
	v_mad_i64_i32 v[162:163], s[56:57], v164, s77, v[156:157]
	s_cselect_b64 s[62:63], -1, 0
	s_lshl_b32 s56, s2, 8
	s_ashr_i32 s57, s56, 31
	v_lshl_add_u64 v[2:3], s[56:57], 1, v[162:163]
	s_mov_b32 s7, s3
	v_lshl_add_u64 v[2:3], v[2:3], 0, s[6:7]
	v_lshl_add_u64 v[166:167], v[2:3], 0, v[160:161]
	s_add_i32 s7, s88, -2
	s_add_u32 s89, s60, 0x100
	v_mov_b32_e32 v1, v0
	v_ashrrev_i32_e32 v165, 31, v164
	s_addc_u32 s90, s61, 0
	v_lshl_add_u64 v[168:169], s[58:59], 0, v[152:153]
	v_lshl_add_u64 v[170:171], s[58:59], 0, v[154:155]
	s_mov_b32 s64, 0
	s_mov_b64 s[60:61], 0
	s_xor_b64 s[62:63], s[62:63], -1
	v_add_u32_e32 v1, s79, v173
	s_add_i32 s2, s64, 2
	ds_read_b128 v[132:135], v1
	ds_read_b128 v[136:139], v1 offset:1024
	ds_read_b128 v[140:143], v1 offset:2048
	ds_read_b128 v[178:181], v1 offset:3072
	v_add_u32_e32 v1, s80, v173
	s_add_u32 s65, s58, s60
	ds_read_b128 v[182:185], v1
	ds_read_b128 v[188:191], v1 offset:1024
	ds_read_b128 v[192:195], v1 offset:2048
	ds_read_b128 v[196:199], v1 offset:3072
	s_addc_u32 s66, s59, s61
	s_add_u32 s65, s65, 0x100
	s_addc_u32 s66, s66, 0
	s_add_u32 s75, s89, s60
	s_addc_u32 s91, s90, s61
	s_cmp_eq_u32 s7, s64
	s_cselect_b32 s67, s51, s66
	s_cselect_b32 s66, s50, s65
	s_cselect_b32 s65, s53, s91
	s_cselect_b32 s64, s52, s75
	v_lshl_add_u64 v[2:3], v[168:169], 0, s[60:61]
	s_add_i32 m0, s69, 0xc000
	ds_read_b128 v[200:203], v174
	ds_read_b128 v[204:207], v174 offset:1024
	ds_read_b128 v[208:211], v174 offset:2048
	ds_read_b128 v[212:215], v174 offset:3072
	ds_read_b128 v[216:219], v174 offset:4096
	ds_read_b128 v[220:223], v174 offset:5120
	ds_read_b128 v[224:227], v174 offset:6144
	ds_read_b128 v[228:231], v174 offset:7168
	global_load_lds_dwordx4 v[2:3], off
	v_lshl_add_u64 v[2:3], v[170:171], 0, s[60:61]
	s_add_i32 m0, s69, 0xe000
	s_nop 0
	global_load_lds_dwordx4 v[2:3], off
	s_waitcnt vmcnt(8)
	s_waitcnt lgkmcnt(0)
	s_waitcnt lgkmcnt(0)
	s_setprio 1
	s_barrier
	v_mfma_f32_16x16x32_bf16 v[128:131], v[132:135], v[200:203], 0
	v_mfma_f32_16x16x32_bf16 v[124:127], v[140:143], v[200:203], 0
	v_mfma_f32_16x16x32_bf16 v[112:115], v[132:135], v[208:211], 0
	v_mfma_f32_16x16x32_bf16 v[108:111], v[140:143], v[208:211], 0
	v_mfma_f32_16x16x32_bf16 v[96:99], v[132:135], v[216:219], 0
	v_mfma_f32_16x16x32_bf16 v[92:95], v[140:143], v[216:219], 0
	v_mfma_f32_16x16x32_bf16 v[80:83], v[132:135], v[224:227], 0
	v_mfma_f32_16x16x32_bf16 v[76:79], v[140:143], v[224:227], 0
	v_mfma_f32_16x16x32_bf16 v[128:131], v[136:139], v[204:207], v[128:131]
	v_mfma_f32_16x16x32_bf16 v[124:127], v[178:181], v[204:207], v[124:127]
	v_mfma_f32_16x16x32_bf16 v[112:115], v[136:139], v[212:215], v[112:115]
	v_mfma_f32_16x16x32_bf16 v[108:111], v[178:181], v[212:215], v[108:111]
	v_mfma_f32_16x16x32_bf16 v[96:99], v[136:139], v[220:223], v[96:99]
	v_mfma_f32_16x16x32_bf16 v[92:95], v[178:181], v[220:223], v[92:95]
	v_mfma_f32_16x16x32_bf16 v[80:83], v[136:139], v[228:231], v[80:83]
	v_mfma_f32_16x16x32_bf16 v[76:79], v[178:181], v[228:231], v[76:79]
	s_setprio 0
	s_setprio 1
	v_mfma_f32_16x16x32_bf16 v[120:123], v[182:185], v[200:203], 0
	v_mfma_f32_16x16x32_bf16 v[116:119], v[192:195], v[200:203], 0
	v_mfma_f32_16x16x32_bf16 v[104:107], v[182:185], v[208:211], 0
	v_mfma_f32_16x16x32_bf16 v[100:103], v[192:195], v[208:211], 0
	v_mfma_f32_16x16x32_bf16 v[88:91], v[182:185], v[216:219], 0
	v_mfma_f32_16x16x32_bf16 v[84:87], v[192:195], v[216:219], 0
	v_mfma_f32_16x16x32_bf16 v[72:75], v[182:185], v[224:227], 0
	v_mfma_f32_16x16x32_bf16 v[68:71], v[192:195], v[224:227], 0
	v_mfma_f32_16x16x32_bf16 v[120:123], v[188:191], v[204:207], v[120:123]
	v_mfma_f32_16x16x32_bf16 v[116:119], v[196:199], v[204:207], v[116:119]
	v_mfma_f32_16x16x32_bf16 v[104:107], v[188:191], v[212:215], v[104:107]
	v_mfma_f32_16x16x32_bf16 v[100:103], v[196:199], v[212:215], v[100:103]
	v_mfma_f32_16x16x32_bf16 v[88:91], v[188:191], v[220:223], v[88:91]
	v_mfma_f32_16x16x32_bf16 v[84:87], v[196:199], v[220:223], v[84:87]
	v_mfma_f32_16x16x32_bf16 v[72:75], v[188:191], v[228:231], v[72:75]
	v_mfma_f32_16x16x32_bf16 v[68:71], v[196:199], v[228:231], v[68:71]
	s_barrier
	s_setprio 0
	s_add_i32 s75, s79, s68
	v_lshl_add_u64 v[232:233], s[64:65], 0, v[148:149]
	s_mov_b32 m0, s75
	ds_read_b128 v[200:203], v174 offset:16384
	ds_read_b128 v[204:207], v174 offset:17408
	ds_read_b128 v[208:211], v174 offset:18432
	ds_read_b128 v[212:215], v174 offset:19456
	ds_read_b128 v[216:219], v174 offset:20480
	ds_read_b128 v[220:223], v174 offset:21504
	ds_read_b128 v[224:227], v174 offset:22528
	ds_read_b128 v[228:231], v174 offset:23552
	global_load_lds_dwordx4 v[232:233], off
	s_add_i32 m0, s75, 0x2000
	s_add_u32 s92, s64, 0xa0000
	v_lshl_add_u64 v[234:235], s[64:65], 0, v[144:145]
	s_addc_u32 s93, s65, 0
	s_add_i32 s75, s80, s68
	global_load_lds_dwordx4 v[234:235], off
	v_lshl_add_u64 v[2:3], s[92:93], 0, v[148:149]
	s_mov_b32 m0, s75
	v_lshl_add_u64 v[236:237], s[66:67], 0, v[150:151]
	global_load_lds_dwordx4 v[2:3], off
	v_lshl_add_u64 v[2:3], s[92:93], 0, v[144:145]
	s_add_i32 m0, s75, 0x2000
	v_lshl_add_u64 v[238:239], s[66:67], 0, v[146:147]
	global_load_lds_dwordx4 v[2:3], off
	s_mov_b32 m0, s69
	s_nop 0
	global_load_lds_dwordx4 v[236:237], off
	s_mov_b32 m0, s70
	s_nop 0
	global_load_lds_dwordx4 v[238:239], off
	s_waitcnt vmcnt(8)
	s_waitcnt lgkmcnt(0)
	s_waitcnt lgkmcnt(0)
	s_setprio 1
	s_barrier
	v_mfma_f32_16x16x32_bf16 v[64:67], v[132:135], v[200:203], 0
	v_mfma_f32_16x16x32_bf16 v[60:63], v[140:143], v[200:203], 0
	v_mfma_f32_16x16x32_bf16 v[48:51], v[132:135], v[208:211], 0
	v_mfma_f32_16x16x32_bf16 v[44:47], v[140:143], v[208:211], 0
	v_mfma_f32_16x16x32_bf16 v[32:35], v[132:135], v[216:219], 0
	v_mfma_f32_16x16x32_bf16 v[28:31], v[140:143], v[216:219], 0
	v_mfma_f32_16x16x32_bf16 v[16:19], v[132:135], v[224:227], 0
	v_mfma_f32_16x16x32_bf16 v[12:15], v[140:143], v[224:227], 0
	v_mfma_f32_16x16x32_bf16 v[64:67], v[136:139], v[204:207], v[64:67]
	v_mfma_f32_16x16x32_bf16 v[60:63], v[178:181], v[204:207], v[60:63]
	v_mfma_f32_16x16x32_bf16 v[48:51], v[136:139], v[212:215], v[48:51]
	v_mfma_f32_16x16x32_bf16 v[44:47], v[178:181], v[212:215], v[44:47]
	v_mfma_f32_16x16x32_bf16 v[32:35], v[136:139], v[220:223], v[32:35]
	v_mfma_f32_16x16x32_bf16 v[28:31], v[178:181], v[220:223], v[28:31]
	v_mfma_f32_16x16x32_bf16 v[16:19], v[136:139], v[228:231], v[16:19]
	v_mfma_f32_16x16x32_bf16 v[12:15], v[178:181], v[228:231], v[12:15]
	s_setprio 0
	s_setprio 1
	v_mfma_f32_16x16x32_bf16 v[56:59], v[182:185], v[200:203], 0
	v_mfma_f32_16x16x32_bf16 v[52:55], v[192:195], v[200:203], 0
	v_mfma_f32_16x16x32_bf16 v[40:43], v[182:185], v[208:211], 0
	v_mfma_f32_16x16x32_bf16 v[36:39], v[192:195], v[208:211], 0
	v_mfma_f32_16x16x32_bf16 v[24:27], v[182:185], v[216:219], 0
	v_mfma_f32_16x16x32_bf16 v[20:23], v[192:195], v[216:219], 0
	v_mfma_f32_16x16x32_bf16 v[8:11], v[182:185], v[224:227], 0
	v_mfma_f32_16x16x32_bf16 v[2:5], v[192:195], v[224:227], 0
	v_mfma_f32_16x16x32_bf16 v[56:59], v[188:191], v[204:207], v[56:59]
	v_mfma_f32_16x16x32_bf16 v[52:55], v[196:199], v[204:207], v[52:55]
	v_mfma_f32_16x16x32_bf16 v[40:43], v[188:191], v[212:215], v[40:43]
	v_mfma_f32_16x16x32_bf16 v[36:39], v[196:199], v[212:215], v[36:39]
	v_mfma_f32_16x16x32_bf16 v[24:27], v[188:191], v[220:223], v[24:27]
	v_mfma_f32_16x16x32_bf16 v[20:23], v[196:199], v[220:223], v[20:23]
	v_mfma_f32_16x16x32_bf16 v[8:11], v[188:191], v[228:231], v[8:11]
	v_mfma_f32_16x16x32_bf16 v[2:5], v[196:199], v[228:231], v[2:5]
	s_barrier
	s_setprio 0
	s_branch .Lpeel_mid_p3
	s_nop 0
	s_nop 0
	s_nop 0
	s_nop 0
	s_nop 0
	s_nop 0
	s_nop 0
	s_nop 0
	s_nop 0
	s_nop 0
	s_nop 0
	s_nop 0

.LBB0_599:
	v_add_u32_e32 v1, s79, v173
	s_add_i32 s2, s64, 2
	ds_read_b128 v[132:135], v1
	ds_read_b128 v[136:139], v1 offset:1024
	ds_read_b128 v[140:143], v1 offset:2048
	ds_read_b128 v[178:181], v1 offset:3072
	v_add_u32_e32 v1, s80, v173
	s_add_u32 s65, s58, s60
	ds_read_b128 v[182:185], v1
	ds_read_b128 v[188:191], v1 offset:1024
	ds_read_b128 v[192:195], v1 offset:2048
	ds_read_b128 v[196:199], v1 offset:3072
	s_addc_u32 s66, s59, s61
	s_add_u32 s65, s65, 0x100
	s_addc_u32 s66, s66, 0
	s_add_u32 s75, s89, s60
	s_addc_u32 s91, s90, s61
	s_cmp_eq_u32 s7, s64
	s_cselect_b32 s67, s51, s66
	s_cselect_b32 s66, s50, s65
	s_cselect_b32 s65, s53, s91
	s_cselect_b32 s64, s52, s75
	v_lshl_add_u64 v[2:3], v[168:169], 0, s[60:61]
	s_add_i32 m0, s69, 0xc000
	ds_read_b128 v[200:203], v174
	ds_read_b128 v[204:207], v174 offset:1024
	ds_read_b128 v[208:211], v174 offset:2048
	ds_read_b128 v[212:215], v174 offset:3072
	ds_read_b128 v[216:219], v174 offset:4096
	ds_read_b128 v[220:223], v174 offset:5120
	ds_read_b128 v[224:227], v174 offset:6144
	ds_read_b128 v[228:231], v174 offset:7168
	global_load_lds_dwordx4 v[2:3], off
	v_lshl_add_u64 v[2:3], v[170:171], 0, s[60:61]
	s_add_i32 m0, s69, 0xe000
	s_nop 0
	global_load_lds_dwordx4 v[2:3], off
	s_waitcnt vmcnt(8)
	s_waitcnt lgkmcnt(0)
	s_waitcnt lgkmcnt(0)
	s_setprio 1
	s_barrier
	v_mfma_f32_16x16x32_bf16 v[128:131], v[132:135], v[200:203], v[128:131]
	v_mfma_f32_16x16x32_bf16 v[124:127], v[140:143], v[200:203], v[124:127]
	v_mfma_f32_16x16x32_bf16 v[112:115], v[132:135], v[208:211], v[112:115]
	v_mfma_f32_16x16x32_bf16 v[108:111], v[140:143], v[208:211], v[108:111]
	v_mfma_f32_16x16x32_bf16 v[96:99], v[132:135], v[216:219], v[96:99]
	v_mfma_f32_16x16x32_bf16 v[92:95], v[140:143], v[216:219], v[92:95]
	v_mfma_f32_16x16x32_bf16 v[80:83], v[132:135], v[224:227], v[80:83]
	v_mfma_f32_16x16x32_bf16 v[76:79], v[140:143], v[224:227], v[76:79]
	v_mfma_f32_16x16x32_bf16 v[128:131], v[136:139], v[204:207], v[128:131]
	v_mfma_f32_16x16x32_bf16 v[124:127], v[178:181], v[204:207], v[124:127]
	v_mfma_f32_16x16x32_bf16 v[112:115], v[136:139], v[212:215], v[112:115]
	v_mfma_f32_16x16x32_bf16 v[108:111], v[178:181], v[212:215], v[108:111]
	v_mfma_f32_16x16x32_bf16 v[96:99], v[136:139], v[220:223], v[96:99]
	v_mfma_f32_16x16x32_bf16 v[92:95], v[178:181], v[220:223], v[92:95]
	v_mfma_f32_16x16x32_bf16 v[80:83], v[136:139], v[228:231], v[80:83]
	v_mfma_f32_16x16x32_bf16 v[76:79], v[178:181], v[228:231], v[76:79]
	s_setprio 0
	s_setprio 1
	v_mfma_f32_16x16x32_bf16 v[120:123], v[182:185], v[200:203], v[120:123]
	v_mfma_f32_16x16x32_bf16 v[116:119], v[192:195], v[200:203], v[116:119]
	v_mfma_f32_16x16x32_bf16 v[104:107], v[182:185], v[208:211], v[104:107]
	v_mfma_f32_16x16x32_bf16 v[100:103], v[192:195], v[208:211], v[100:103]
	v_mfma_f32_16x16x32_bf16 v[88:91], v[182:185], v[216:219], v[88:91]
	v_mfma_f32_16x16x32_bf16 v[84:87], v[192:195], v[216:219], v[84:87]
	v_mfma_f32_16x16x32_bf16 v[72:75], v[182:185], v[224:227], v[72:75]
	v_mfma_f32_16x16x32_bf16 v[68:71], v[192:195], v[224:227], v[68:71]
	v_mfma_f32_16x16x32_bf16 v[120:123], v[188:191], v[204:207], v[120:123]
	v_mfma_f32_16x16x32_bf16 v[116:119], v[196:199], v[204:207], v[116:119]
	v_mfma_f32_16x16x32_bf16 v[104:107], v[188:191], v[212:215], v[104:107]
	v_mfma_f32_16x16x32_bf16 v[100:103], v[196:199], v[212:215], v[100:103]
	v_mfma_f32_16x16x32_bf16 v[88:91], v[188:191], v[220:223], v[88:91]
	v_mfma_f32_16x16x32_bf16 v[84:87], v[196:199], v[220:223], v[84:87]
	v_mfma_f32_16x16x32_bf16 v[72:75], v[188:191], v[228:231], v[72:75]
	v_mfma_f32_16x16x32_bf16 v[68:71], v[196:199], v[228:231], v[68:71]
	s_barrier
	s_setprio 0
	s_add_i32 s75, s79, s68
	v_lshl_add_u64 v[232:233], s[64:65], 0, v[148:149]
	s_mov_b32 m0, s75
	ds_read_b128 v[200:203], v174 offset:16384
	ds_read_b128 v[204:207], v174 offset:17408
	ds_read_b128 v[208:211], v174 offset:18432
	ds_read_b128 v[212:215], v174 offset:19456
	ds_read_b128 v[216:219], v174 offset:20480
	ds_read_b128 v[220:223], v174 offset:21504
	ds_read_b128 v[224:227], v174 offset:22528
	ds_read_b128 v[228:231], v174 offset:23552
	global_load_lds_dwordx4 v[232:233], off
	s_add_i32 m0, s75, 0x2000
	s_add_u32 s92, s64, 0xa0000
	v_lshl_add_u64 v[234:235], s[64:65], 0, v[144:145]
	s_addc_u32 s93, s65, 0
	s_add_i32 s75, s80, s68
	global_load_lds_dwordx4 v[234:235], off
	v_lshl_add_u64 v[2:3], s[92:93], 0, v[148:149]
	s_mov_b32 m0, s75
	v_lshl_add_u64 v[236:237], s[66:67], 0, v[150:151]
	global_load_lds_dwordx4 v[2:3], off
	v_lshl_add_u64 v[2:3], s[92:93], 0, v[144:145]
	s_add_i32 m0, s75, 0x2000
	v_lshl_add_u64 v[238:239], s[66:67], 0, v[146:147]
	global_load_lds_dwordx4 v[2:3], off
	s_mov_b32 m0, s69
	s_nop 0
	global_load_lds_dwordx4 v[236:237], off
	s_mov_b32 m0, s70
	s_nop 0
	global_load_lds_dwordx4 v[238:239], off
	s_waitcnt vmcnt(8)
	s_waitcnt lgkmcnt(0)
	s_waitcnt lgkmcnt(0)
	s_setprio 1
	s_barrier
	v_mfma_f32_16x16x32_bf16 v[64:67], v[132:135], v[200:203], v[64:67]
	v_mfma_f32_16x16x32_bf16 v[60:63], v[140:143], v[200:203], v[60:63]
	v_mfma_f32_16x16x32_bf16 v[48:51], v[132:135], v[208:211], v[48:51]
	v_mfma_f32_16x16x32_bf16 v[44:47], v[140:143], v[208:211], v[44:47]
	v_mfma_f32_16x16x32_bf16 v[32:35], v[132:135], v[216:219], v[32:35]
	v_mfma_f32_16x16x32_bf16 v[28:31], v[140:143], v[216:219], v[28:31]
	v_mfma_f32_16x16x32_bf16 v[16:19], v[132:135], v[224:227], v[16:19]
	v_mfma_f32_16x16x32_bf16 v[12:15], v[140:143], v[224:227], v[12:15]
	v_mfma_f32_16x16x32_bf16 v[64:67], v[136:139], v[204:207], v[64:67]
	v_mfma_f32_16x16x32_bf16 v[60:63], v[178:181], v[204:207], v[60:63]
	v_mfma_f32_16x16x32_bf16 v[48:51], v[136:139], v[212:215], v[48:51]
	v_mfma_f32_16x16x32_bf16 v[44:47], v[178:181], v[212:215], v[44:47]
	v_mfma_f32_16x16x32_bf16 v[32:35], v[136:139], v[220:223], v[32:35]
	v_mfma_f32_16x16x32_bf16 v[28:31], v[178:181], v[220:223], v[28:31]
	v_mfma_f32_16x16x32_bf16 v[16:19], v[136:139], v[228:231], v[16:19]
	v_mfma_f32_16x16x32_bf16 v[12:15], v[178:181], v[228:231], v[12:15]
	s_setprio 0
	s_setprio 1
	v_mfma_f32_16x16x32_bf16 v[56:59], v[182:185], v[200:203], v[56:59]
	v_mfma_f32_16x16x32_bf16 v[52:55], v[192:195], v[200:203], v[52:55]
	v_mfma_f32_16x16x32_bf16 v[40:43], v[182:185], v[208:211], v[40:43]
	v_mfma_f32_16x16x32_bf16 v[36:39], v[192:195], v[208:211], v[36:39]
	v_mfma_f32_16x16x32_bf16 v[24:27], v[182:185], v[216:219], v[24:27]
	v_mfma_f32_16x16x32_bf16 v[20:23], v[192:195], v[216:219], v[20:23]
	v_mfma_f32_16x16x32_bf16 v[8:11], v[182:185], v[224:227], v[8:11]
	v_mfma_f32_16x16x32_bf16 v[2:5], v[192:195], v[224:227], v[4:7]
	v_mfma_f32_16x16x32_bf16 v[56:59], v[188:191], v[204:207], v[56:59]
	v_mfma_f32_16x16x32_bf16 v[52:55], v[196:199], v[204:207], v[52:55]
	v_mfma_f32_16x16x32_bf16 v[40:43], v[188:191], v[212:215], v[40:43]
	v_mfma_f32_16x16x32_bf16 v[36:39], v[196:199], v[212:215], v[36:39]
	v_mfma_f32_16x16x32_bf16 v[24:27], v[188:191], v[220:223], v[24:27]
	v_mfma_f32_16x16x32_bf16 v[20:23], v[196:199], v[220:223], v[20:23]
	v_mfma_f32_16x16x32_bf16 v[8:11], v[188:191], v[228:231], v[8:11]
	v_mfma_f32_16x16x32_bf16 v[2:5], v[196:199], v[228:231], v[2:5]
	s_barrier
	s_setprio 0
.Lpeel_mid_p3:
	s_add_i32 s75, 0, 0x18000
	v_add_u32_e32 v1, s75, v173
	s_add_i32 s91, 0, 0x1c000
	ds_read_b128 v[132:135], v1
	ds_read_b128 v[136:139], v1 offset:1024
	ds_read_b128 v[140:143], v1 offset:2048
	ds_read_b128 v[178:181], v1 offset:3072
	v_add_u32_e32 v1, s91, v173
	ds_read_b128 v[182:185], v1
	ds_read_b128 v[188:191], v1 offset:1024
	ds_read_b128 v[192:195], v1 offset:2048
	ds_read_b128 v[196:199], v1 offset:3072
	s_add_u32 s66, s66, 0xa0000
	s_addc_u32 s67, s67, 0
	s_mov_b32 m0, s71
	v_lshl_add_u64 v[6:7], s[66:67], 0, v[150:151]
	ds_read_b128 v[200:203], v174 offset:32768
	ds_read_b128 v[204:207], v174 offset:33792
	ds_read_b128 v[208:211], v174 offset:34816
	ds_read_b128 v[212:215], v174 offset:35840
	ds_read_b128 v[216:219], v174 offset:36864
	ds_read_b128 v[220:223], v174 offset:37888
	ds_read_b128 v[224:227], v174 offset:38912
	ds_read_b128 v[228:231], v174 offset:39936
	global_load_lds_dwordx4 v[6:7], off
	v_lshl_add_u64 v[6:7], s[66:67], 0, v[146:147]
	s_mov_b32 m0, s72
	s_nop 0
	global_load_lds_dwordx4 v[6:7], off
	s_waitcnt vmcnt(8)
	s_waitcnt lgkmcnt(0)
	s_waitcnt lgkmcnt(0)
	s_setprio 1
	s_barrier
	v_mfma_f32_16x16x32_bf16 v[128:131], v[132:135], v[200:203], v[128:131]
	v_mfma_f32_16x16x32_bf16 v[124:127], v[140:143], v[200:203], v[124:127]
	v_mfma_f32_16x16x32_bf16 v[112:115], v[132:135], v[208:211], v[112:115]
	v_mfma_f32_16x16x32_bf16 v[108:111], v[140:143], v[208:211], v[108:111]
	v_mfma_f32_16x16x32_bf16 v[96:99], v[132:135], v[216:219], v[96:99]
	v_mfma_f32_16x16x32_bf16 v[92:95], v[140:143], v[216:219], v[92:95]
	v_mfma_f32_16x16x32_bf16 v[80:83], v[132:135], v[224:227], v[80:83]
	v_mfma_f32_16x16x32_bf16 v[76:79], v[140:143], v[224:227], v[76:79]
	v_mfma_f32_16x16x32_bf16 v[128:131], v[136:139], v[204:207], v[128:131]
	v_mfma_f32_16x16x32_bf16 v[124:127], v[178:181], v[204:207], v[124:127]
	v_mfma_f32_16x16x32_bf16 v[112:115], v[136:139], v[212:215], v[112:115]
	v_mfma_f32_16x16x32_bf16 v[108:111], v[178:181], v[212:215], v[108:111]
	v_mfma_f32_16x16x32_bf16 v[96:99], v[136:139], v[220:223], v[96:99]
	v_mfma_f32_16x16x32_bf16 v[92:95], v[178:181], v[220:223], v[92:95]
	v_mfma_f32_16x16x32_bf16 v[80:83], v[136:139], v[228:231], v[80:83]
	v_mfma_f32_16x16x32_bf16 v[76:79], v[178:181], v[228:231], v[76:79]
	s_setprio 0
	s_setprio 1
	v_mfma_f32_16x16x32_bf16 v[120:123], v[182:185], v[200:203], v[120:123]
	v_mfma_f32_16x16x32_bf16 v[116:119], v[192:195], v[200:203], v[116:119]
	v_mfma_f32_16x16x32_bf16 v[104:107], v[182:185], v[208:211], v[104:107]
	v_mfma_f32_16x16x32_bf16 v[100:103], v[192:195], v[208:211], v[100:103]
	v_mfma_f32_16x16x32_bf16 v[88:91], v[182:185], v[216:219], v[88:91]
	v_mfma_f32_16x16x32_bf16 v[84:87], v[192:195], v[216:219], v[84:87]
	v_mfma_f32_16x16x32_bf16 v[72:75], v[182:185], v[224:227], v[72:75]
	v_mfma_f32_16x16x32_bf16 v[68:71], v[192:195], v[224:227], v[68:71]
	v_mfma_f32_16x16x32_bf16 v[120:123], v[188:191], v[204:207], v[120:123]
	v_mfma_f32_16x16x32_bf16 v[116:119], v[196:199], v[204:207], v[116:119]
	v_mfma_f32_16x16x32_bf16 v[104:107], v[188:191], v[212:215], v[104:107]
	v_mfma_f32_16x16x32_bf16 v[100:103], v[196:199], v[212:215], v[100:103]
	v_mfma_f32_16x16x32_bf16 v[88:91], v[188:191], v[220:223], v[88:91]
	v_mfma_f32_16x16x32_bf16 v[84:87], v[196:199], v[220:223], v[84:87]
	v_mfma_f32_16x16x32_bf16 v[72:75], v[188:191], v[228:231], v[72:75]
	v_mfma_f32_16x16x32_bf16 v[68:71], v[196:199], v[228:231], v[68:71]
	s_barrier
	s_setprio 0
	s_add_i32 s66, s75, s68
	v_lshl_add_u64 v[6:7], v[232:233], 0, s[14:15]
	s_mov_b32 m0, s66
	ds_read_b128 v[200:203], v174 offset:49152
	ds_read_b128 v[204:207], v174 offset:50176
	ds_read_b128 v[208:211], v174 offset:51200
	ds_read_b128 v[212:215], v174 offset:52224
	ds_read_b128 v[216:219], v174 offset:53248
	ds_read_b128 v[220:223], v174 offset:54272
	ds_read_b128 v[224:227], v174 offset:55296
	ds_read_b128 v[228:231], v174 offset:56320
	global_load_lds_dwordx4 v[6:7], off
	s_add_i32 m0, s66, 0x2000
	s_add_u32 s64, s64, 0xa0080
	v_lshl_add_u64 v[6:7], v[234:235], 0, s[14:15]
	s_addc_u32 s65, s65, 0
	s_add_i32 s66, s91, s68
	global_load_lds_dwordx4 v[6:7], off
	v_lshl_add_u64 v[6:7], s[64:65], 0, v[148:149]
	s_mov_b32 m0, s66
	s_nop 0
	global_load_lds_dwordx4 v[6:7], off
	v_lshl_add_u64 v[6:7], s[64:65], 0, v[144:145]
	s_add_i32 m0, s66, 0x2000
	s_nop 0
	global_load_lds_dwordx4 v[6:7], off
	v_lshl_add_u64 v[6:7], v[236:237], 0, s[14:15]
	s_mov_b32 m0, s73
	s_nop 0
	global_load_lds_dwordx4 v[6:7], off
	v_lshl_add_u64 v[6:7], v[238:239], 0, s[14:15]
	s_mov_b32 m0, s76
	s_nop 0
	global_load_lds_dwordx4 v[6:7], off
	s_waitcnt vmcnt(8)
	s_waitcnt lgkmcnt(0)
	s_waitcnt lgkmcnt(0)
	s_setprio 1
	s_barrier
	v_mfma_f32_16x16x32_bf16 v[64:67], v[132:135], v[200:203], v[64:67]
	v_mfma_f32_16x16x32_bf16 v[60:63], v[140:143], v[200:203], v[60:63]
	v_mfma_f32_16x16x32_bf16 v[48:51], v[132:135], v[208:211], v[48:51]
	v_mfma_f32_16x16x32_bf16 v[44:47], v[140:143], v[208:211], v[44:47]
	v_mfma_f32_16x16x32_bf16 v[32:35], v[132:135], v[216:219], v[32:35]
	v_mfma_f32_16x16x32_bf16 v[28:31], v[140:143], v[216:219], v[28:31]
	v_mfma_f32_16x16x32_bf16 v[16:19], v[132:135], v[224:227], v[16:19]
	v_mfma_f32_16x16x32_bf16 v[12:15], v[140:143], v[224:227], v[12:15]
	v_mfma_f32_16x16x32_bf16 v[64:67], v[136:139], v[204:207], v[64:67]
	v_mfma_f32_16x16x32_bf16 v[60:63], v[178:181], v[204:207], v[60:63]
	v_mfma_f32_16x16x32_bf16 v[48:51], v[136:139], v[212:215], v[48:51]
	v_mfma_f32_16x16x32_bf16 v[44:47], v[178:181], v[212:215], v[44:47]
	v_mfma_f32_16x16x32_bf16 v[32:35], v[136:139], v[220:223], v[32:35]
	v_mfma_f32_16x16x32_bf16 v[28:31], v[178:181], v[220:223], v[28:31]
	v_mfma_f32_16x16x32_bf16 v[16:19], v[136:139], v[228:231], v[16:19]
	v_mfma_f32_16x16x32_bf16 v[12:15], v[178:181], v[228:231], v[12:15]
	s_setprio 0
	s_setprio 1
	v_mfma_f32_16x16x32_bf16 v[56:59], v[182:185], v[200:203], v[56:59]
	v_mfma_f32_16x16x32_bf16 v[52:55], v[192:195], v[200:203], v[52:55]
	v_mfma_f32_16x16x32_bf16 v[40:43], v[182:185], v[208:211], v[40:43]
	v_mfma_f32_16x16x32_bf16 v[36:39], v[192:195], v[208:211], v[36:39]
	v_mfma_f32_16x16x32_bf16 v[24:27], v[182:185], v[216:219], v[24:27]
	v_mfma_f32_16x16x32_bf16 v[20:23], v[192:195], v[216:219], v[20:23]
	v_mfma_f32_16x16x32_bf16 v[6:9], v[182:185], v[224:227], v[8:11]
	v_mfma_f32_16x16x32_bf16 v[2:5], v[192:195], v[224:227], v[2:5]
	v_mfma_f32_16x16x32_bf16 v[56:59], v[188:191], v[204:207], v[56:59]
	v_mfma_f32_16x16x32_bf16 v[52:55], v[196:199], v[204:207], v[52:55]
	v_mfma_f32_16x16x32_bf16 v[40:43], v[188:191], v[212:215], v[40:43]
	v_mfma_f32_16x16x32_bf16 v[36:39], v[196:199], v[212:215], v[36:39]
	v_mfma_f32_16x16x32_bf16 v[24:27], v[188:191], v[220:223], v[24:27]
	v_mfma_f32_16x16x32_bf16 v[20:23], v[196:199], v[220:223], v[20:23]
	v_mfma_f32_16x16x32_bf16 v[8:11], v[188:191], v[228:231], v[6:9]
	v_mfma_f32_16x16x32_bf16 v[4:7], v[196:199], v[228:231], v[2:5]
	s_setprio 0
	s_and_b64 vcc, exec, s[18:19]
	s_cbranch_vccnz .Lhk_skipB
	s_and_b64 vcc, exec, s[62:63]
	s_cbranch_vccnz .Lhk_skipB
	s_cmp_eq_u32 s2, 16
	s_cbranch_scc1 .Lhk_doB
	s_cmp_eq_u32 s2, 24
	s_cbranch_scc0 .Lhk_skipB

.LBB0_671:
	s_add_u32 s6, s6, 0x80080
	s_addc_u32 s7, s7, 0
	s_add_u32 s5, s40, 0x100
	s_addc_u32 s25, s41, 0
	s_mov_b32 s56, -2
	ds_read_b128 v[128:131], v185
	ds_read_b128 v[132:135], v185 offset:1024
	ds_read_b128 v[136:139], v185 offset:2048
	ds_read_b128 v[140:143], v185 offset:3072
	ds_read_b128 v[162:165], v186
	ds_read_b128 v[166:169], v186 offset:1024
	ds_read_b128 v[170:173], v186 offset:2048
	ds_read_b128 v[174:177], v186 offset:3072
	s_add_u32 s38, s6, 0xfff80080
	s_addc_u32 s39, s7, -1
	s_cmp_eq_u32 s56, 28
	s_cselect_b32 s41, s27, s39
	s_cselect_b32 s40, s26, s38
	s_cselect_b32 s39, s23, s25
	s_cselect_b32 s38, s22, s5
	v_lshl_add_u64 v[182:183], s[6:7], 0, v[158:159]
	s_add_i32 m0, s42, 0xc000
	ds_read_b128 v[178:181], v188
	ds_read_b128 v[192:195], v188 offset:1024
	ds_read_b128 v[196:199], v188 offset:2048
	ds_read_b128 v[200:203], v188 offset:3072
	ds_read_b128 v[204:207], v188 offset:4096
	ds_read_b128 v[208:211], v188 offset:5120
	ds_read_b128 v[212:215], v188 offset:6144
	ds_read_b128 v[216:219], v188 offset:7168
	global_load_lds_dwordx4 v[182:183], off
	v_lshl_add_u64 v[182:183], s[6:7], 0, v[160:161]
	s_add_i32 m0, s42, 0xe000
	s_nop 0
	global_load_lds_dwordx4 v[182:183], off
	s_waitcnt vmcnt(8)
	s_waitcnt lgkmcnt(0)
	s_waitcnt lgkmcnt(0)
	s_setprio 1
	s_barrier
	v_mfma_f32_16x16x32_bf16 v[124:127], v[128:131], v[178:181], 0
	v_mfma_f32_16x16x32_bf16 v[120:123], v[136:139], v[178:181], 0
	v_mfma_f32_16x16x32_bf16 v[108:111], v[128:131], v[196:199], 0
	v_mfma_f32_16x16x32_bf16 v[104:107], v[136:139], v[196:199], 0
	v_mfma_f32_16x16x32_bf16 v[92:95], v[128:131], v[204:207], 0
	v_mfma_f32_16x16x32_bf16 v[88:91], v[136:139], v[204:207], 0
	v_mfma_f32_16x16x32_bf16 v[76:79], v[128:131], v[212:215], 0
	v_mfma_f32_16x16x32_bf16 v[72:75], v[136:139], v[212:215], 0
	v_mfma_f32_16x16x32_bf16 v[124:127], v[132:135], v[192:195], v[124:127]
	v_mfma_f32_16x16x32_bf16 v[120:123], v[140:143], v[192:195], v[120:123]
	v_mfma_f32_16x16x32_bf16 v[108:111], v[132:135], v[200:203], v[108:111]
	v_mfma_f32_16x16x32_bf16 v[104:107], v[140:143], v[200:203], v[104:107]
	v_mfma_f32_16x16x32_bf16 v[92:95], v[132:135], v[208:211], v[92:95]
	v_mfma_f32_16x16x32_bf16 v[88:91], v[140:143], v[208:211], v[88:91]
	v_mfma_f32_16x16x32_bf16 v[76:79], v[132:135], v[216:219], v[76:79]
	v_mfma_f32_16x16x32_bf16 v[72:75], v[140:143], v[216:219], v[72:75]
	s_setprio 0
	s_setprio 1
	v_mfma_f32_16x16x32_bf16 v[116:119], v[162:165], v[178:181], 0
	v_mfma_f32_16x16x32_bf16 v[112:115], v[170:173], v[178:181], 0
	v_mfma_f32_16x16x32_bf16 v[100:103], v[162:165], v[196:199], 0
	v_mfma_f32_16x16x32_bf16 v[96:99], v[170:173], v[196:199], 0
	v_mfma_f32_16x16x32_bf16 v[84:87], v[162:165], v[204:207], 0
	v_mfma_f32_16x16x32_bf16 v[80:83], v[170:173], v[204:207], 0
	v_mfma_f32_16x16x32_bf16 v[68:71], v[162:165], v[212:215], 0
	v_mfma_f32_16x16x32_bf16 v[64:67], v[170:173], v[212:215], 0
	v_mfma_f32_16x16x32_bf16 v[116:119], v[166:169], v[192:195], v[116:119]
	v_mfma_f32_16x16x32_bf16 v[112:115], v[174:177], v[192:195], v[112:115]
	v_mfma_f32_16x16x32_bf16 v[100:103], v[166:169], v[200:203], v[100:103]
	v_mfma_f32_16x16x32_bf16 v[96:99], v[174:177], v[200:203], v[96:99]
	v_mfma_f32_16x16x32_bf16 v[84:87], v[166:169], v[208:211], v[84:87]
	v_mfma_f32_16x16x32_bf16 v[80:83], v[174:177], v[208:211], v[80:83]
	v_mfma_f32_16x16x32_bf16 v[68:71], v[166:169], v[216:219], v[68:71]
	v_mfma_f32_16x16x32_bf16 v[64:67], v[174:177], v[216:219], v[64:67]
	s_barrier
	s_setprio 0
	s_add_i32 s57, s51, s35
	v_lshl_add_u64 v[182:183], s[38:39], 0, v[148:149]
	s_mov_b32 m0, s57
	ds_read_b128 v[178:181], v188 offset:16384
	ds_read_b128 v[192:195], v188 offset:17408
	ds_read_b128 v[196:199], v188 offset:18432
	ds_read_b128 v[200:203], v188 offset:19456
	ds_read_b128 v[204:207], v188 offset:20480
	ds_read_b128 v[208:211], v188 offset:21504
	ds_read_b128 v[212:215], v188 offset:22528
	ds_read_b128 v[216:219], v188 offset:23552
	global_load_lds_dwordx4 v[182:183], off
	s_add_i32 m0, s57, 0x2000
	s_add_u32 s58, s38, 0x80000
	v_lshl_add_u64 v[220:221], s[38:39], 0, v[144:145]
	s_addc_u32 s59, s39, 0
	s_add_i32 s57, s52, s35
	global_load_lds_dwordx4 v[220:221], off
	v_lshl_add_u64 v[222:223], s[58:59], 0, v[148:149]
	s_mov_b32 m0, s57
	v_lshl_add_u64 v[224:225], s[40:41], 0, v[146:147]
	global_load_lds_dwordx4 v[222:223], off
	v_lshl_add_u64 v[222:223], s[58:59], 0, v[144:145]
	s_add_i32 m0, s57, 0x2000
	s_nop 0
	global_load_lds_dwordx4 v[222:223], off
	v_lshl_add_u64 v[222:223], s[40:41], 0, v[150:151]
	s_mov_b32 m0, s42
	s_nop 0
	global_load_lds_dwordx4 v[222:223], off
	s_mov_b32 m0, s43
	s_nop 0
	global_load_lds_dwordx4 v[224:225], off
	s_waitcnt vmcnt(8)
	s_waitcnt lgkmcnt(0)
	s_waitcnt lgkmcnt(0)
	s_setprio 1
	s_barrier
	v_mfma_f32_16x16x32_bf16 v[60:63], v[128:131], v[178:181], 0
	v_mfma_f32_16x16x32_bf16 v[56:59], v[136:139], v[178:181], 0
	v_mfma_f32_16x16x32_bf16 v[44:47], v[128:131], v[196:199], 0
	v_mfma_f32_16x16x32_bf16 v[40:43], v[136:139], v[196:199], 0
	v_mfma_f32_16x16x32_bf16 v[28:31], v[128:131], v[204:207], 0
	v_mfma_f32_16x16x32_bf16 v[24:27], v[136:139], v[204:207], 0
	v_mfma_f32_16x16x32_bf16 v[12:15], v[128:131], v[212:215], 0
	v_mfma_f32_16x16x32_bf16 v[8:11], v[136:139], v[212:215], 0
	v_mfma_f32_16x16x32_bf16 v[60:63], v[132:135], v[192:195], v[60:63]
	v_mfma_f32_16x16x32_bf16 v[56:59], v[140:143], v[192:195], v[56:59]
	v_mfma_f32_16x16x32_bf16 v[44:47], v[132:135], v[200:203], v[44:47]
	v_mfma_f32_16x16x32_bf16 v[40:43], v[140:143], v[200:203], v[40:43]
	v_mfma_f32_16x16x32_bf16 v[28:31], v[132:135], v[208:211], v[28:31]
	v_mfma_f32_16x16x32_bf16 v[24:27], v[140:143], v[208:211], v[24:27]
	v_mfma_f32_16x16x32_bf16 v[12:15], v[132:135], v[216:219], v[12:15]
	v_mfma_f32_16x16x32_bf16 v[8:11], v[140:143], v[216:219], v[8:11]
	s_setprio 0
	s_setprio 1
	v_mfma_f32_16x16x32_bf16 v[52:55], v[162:165], v[178:181], 0
	v_mfma_f32_16x16x32_bf16 v[48:51], v[170:173], v[178:181], 0
	v_mfma_f32_16x16x32_bf16 v[36:39], v[162:165], v[196:199], 0
	v_mfma_f32_16x16x32_bf16 v[32:35], v[170:173], v[196:199], 0
	v_mfma_f32_16x16x32_bf16 v[20:23], v[162:165], v[204:207], 0
	v_mfma_f32_16x16x32_bf16 v[16:19], v[170:173], v[204:207], 0
	v_mfma_f32_16x16x32_bf16 v[4:7], v[162:165], v[212:215], 0
	v_mfma_f32_16x16x32_bf16 v[0:3], v[170:173], v[212:215], 0
	v_mfma_f32_16x16x32_bf16 v[52:55], v[166:169], v[192:195], v[52:55]
	v_mfma_f32_16x16x32_bf16 v[48:51], v[174:177], v[192:195], v[48:51]
	v_mfma_f32_16x16x32_bf16 v[36:39], v[166:169], v[200:203], v[36:39]
	v_mfma_f32_16x16x32_bf16 v[32:35], v[174:177], v[200:203], v[32:35]
	v_mfma_f32_16x16x32_bf16 v[20:23], v[166:169], v[208:211], v[20:23]
	v_mfma_f32_16x16x32_bf16 v[16:19], v[174:177], v[208:211], v[16:19]
	v_mfma_f32_16x16x32_bf16 v[4:7], v[166:169], v[216:219], v[4:7]
	v_mfma_f32_16x16x32_bf16 v[0:3], v[174:177], v[216:219], v[0:3]
	s_barrier
	s_setprio 0
	s_branch .Lpeel_mid_p4
.LBB0_672:
	ds_read_b128 v[128:131], v185
	ds_read_b128 v[132:135], v185 offset:1024
	ds_read_b128 v[136:139], v185 offset:2048
	ds_read_b128 v[140:143], v185 offset:3072
	ds_read_b128 v[162:165], v186
	ds_read_b128 v[166:169], v186 offset:1024
	ds_read_b128 v[170:173], v186 offset:2048
	ds_read_b128 v[174:177], v186 offset:3072
	s_add_u32 s38, s6, 0xfff80080
	s_addc_u32 s39, s7, -1
	s_cmp_eq_u32 s56, 28
	s_cselect_b32 s41, s27, s39
	s_cselect_b32 s40, s26, s38
	s_cselect_b32 s39, s23, s25
	s_cselect_b32 s38, s22, s5
	v_lshl_add_u64 v[182:183], s[6:7], 0, v[158:159]
	s_add_i32 m0, s42, 0xc000
	ds_read_b128 v[178:181], v188
	ds_read_b128 v[192:195], v188 offset:1024
	ds_read_b128 v[196:199], v188 offset:2048
	ds_read_b128 v[200:203], v188 offset:3072
	ds_read_b128 v[204:207], v188 offset:4096
	ds_read_b128 v[208:211], v188 offset:5120
	ds_read_b128 v[212:215], v188 offset:6144
	ds_read_b128 v[216:219], v188 offset:7168
	global_load_lds_dwordx4 v[182:183], off
	v_lshl_add_u64 v[182:183], s[6:7], 0, v[160:161]
	s_add_i32 m0, s42, 0xe000
	s_nop 0
	global_load_lds_dwordx4 v[182:183], off
	s_waitcnt vmcnt(8)
	s_waitcnt lgkmcnt(0)
	s_waitcnt lgkmcnt(0)
	s_setprio 1
	s_barrier
	v_mfma_f32_16x16x32_bf16 v[124:127], v[128:131], v[178:181], v[124:127]
	v_mfma_f32_16x16x32_bf16 v[120:123], v[136:139], v[178:181], v[120:123]
	v_mfma_f32_16x16x32_bf16 v[108:111], v[128:131], v[196:199], v[108:111]
	v_mfma_f32_16x16x32_bf16 v[104:107], v[136:139], v[196:199], v[104:107]
	v_mfma_f32_16x16x32_bf16 v[92:95], v[128:131], v[204:207], v[92:95]
	v_mfma_f32_16x16x32_bf16 v[88:91], v[136:139], v[204:207], v[88:91]
	v_mfma_f32_16x16x32_bf16 v[76:79], v[128:131], v[212:215], v[76:79]
	v_mfma_f32_16x16x32_bf16 v[72:75], v[136:139], v[212:215], v[72:75]
	v_mfma_f32_16x16x32_bf16 v[124:127], v[132:135], v[192:195], v[124:127]
	v_mfma_f32_16x16x32_bf16 v[120:123], v[140:143], v[192:195], v[120:123]
	v_mfma_f32_16x16x32_bf16 v[108:111], v[132:135], v[200:203], v[108:111]
	v_mfma_f32_16x16x32_bf16 v[104:107], v[140:143], v[200:203], v[104:107]
	v_mfma_f32_16x16x32_bf16 v[92:95], v[132:135], v[208:211], v[92:95]
	v_mfma_f32_16x16x32_bf16 v[88:91], v[140:143], v[208:211], v[88:91]
	v_mfma_f32_16x16x32_bf16 v[76:79], v[132:135], v[216:219], v[76:79]
	v_mfma_f32_16x16x32_bf16 v[72:75], v[140:143], v[216:219], v[72:75]
	s_setprio 0
	s_setprio 1
	v_mfma_f32_16x16x32_bf16 v[116:119], v[162:165], v[178:181], v[116:119]
	v_mfma_f32_16x16x32_bf16 v[112:115], v[170:173], v[178:181], v[112:115]
	v_mfma_f32_16x16x32_bf16 v[100:103], v[162:165], v[196:199], v[100:103]
	v_mfma_f32_16x16x32_bf16 v[96:99], v[170:173], v[196:199], v[96:99]
	v_mfma_f32_16x16x32_bf16 v[84:87], v[162:165], v[204:207], v[84:87]
	v_mfma_f32_16x16x32_bf16 v[80:83], v[170:173], v[204:207], v[80:83]
	v_mfma_f32_16x16x32_bf16 v[68:71], v[162:165], v[212:215], v[68:71]
	v_mfma_f32_16x16x32_bf16 v[64:67], v[170:173], v[212:215], v[64:67]
	v_mfma_f32_16x16x32_bf16 v[116:119], v[166:169], v[192:195], v[116:119]
	v_mfma_f32_16x16x32_bf16 v[112:115], v[174:177], v[192:195], v[112:115]
	v_mfma_f32_16x16x32_bf16 v[100:103], v[166:169], v[200:203], v[100:103]
	v_mfma_f32_16x16x32_bf16 v[96:99], v[174:177], v[200:203], v[96:99]
	v_mfma_f32_16x16x32_bf16 v[84:87], v[166:169], v[208:211], v[84:87]
	v_mfma_f32_16x16x32_bf16 v[80:83], v[174:177], v[208:211], v[80:83]
	v_mfma_f32_16x16x32_bf16 v[68:71], v[166:169], v[216:219], v[68:71]
	v_mfma_f32_16x16x32_bf16 v[64:67], v[174:177], v[216:219], v[64:67]
	s_barrier
	s_setprio 0
	s_add_i32 s57, s51, s35
	v_lshl_add_u64 v[182:183], s[38:39], 0, v[148:149]
	s_mov_b32 m0, s57
	ds_read_b128 v[178:181], v188 offset:16384
	ds_read_b128 v[192:195], v188 offset:17408
	ds_read_b128 v[196:199], v188 offset:18432
	ds_read_b128 v[200:203], v188 offset:19456
	ds_read_b128 v[204:207], v188 offset:20480
	ds_read_b128 v[208:211], v188 offset:21504
	ds_read_b128 v[212:215], v188 offset:22528
	ds_read_b128 v[216:219], v188 offset:23552
	global_load_lds_dwordx4 v[182:183], off
	s_add_i32 m0, s57, 0x2000
	s_add_u32 s58, s38, 0x80000
	v_lshl_add_u64 v[220:221], s[38:39], 0, v[144:145]
	s_addc_u32 s59, s39, 0
	s_add_i32 s57, s52, s35
	global_load_lds_dwordx4 v[220:221], off
	v_lshl_add_u64 v[222:223], s[58:59], 0, v[148:149]
	s_mov_b32 m0, s57
	v_lshl_add_u64 v[224:225], s[40:41], 0, v[146:147]
	global_load_lds_dwordx4 v[222:223], off
	v_lshl_add_u64 v[222:223], s[58:59], 0, v[144:145]
	s_add_i32 m0, s57, 0x2000
	s_nop 0
	global_load_lds_dwordx4 v[222:223], off
	v_lshl_add_u64 v[222:223], s[40:41], 0, v[150:151]
	s_mov_b32 m0, s42
	s_nop 0
	global_load_lds_dwordx4 v[222:223], off
	s_mov_b32 m0, s43
	s_nop 0
	global_load_lds_dwordx4 v[224:225], off
	s_waitcnt vmcnt(8)
	s_waitcnt lgkmcnt(0)
	s_waitcnt lgkmcnt(0)
	s_setprio 1
	s_barrier
	v_mfma_f32_16x16x32_bf16 v[60:63], v[128:131], v[178:181], v[60:63]
	v_mfma_f32_16x16x32_bf16 v[56:59], v[136:139], v[178:181], v[56:59]
	v_mfma_f32_16x16x32_bf16 v[44:47], v[128:131], v[196:199], v[44:47]
	v_mfma_f32_16x16x32_bf16 v[40:43], v[136:139], v[196:199], v[40:43]
	v_mfma_f32_16x16x32_bf16 v[28:31], v[128:131], v[204:207], v[28:31]
	v_mfma_f32_16x16x32_bf16 v[24:27], v[136:139], v[204:207], v[24:27]
	v_mfma_f32_16x16x32_bf16 v[12:15], v[128:131], v[212:215], v[12:15]
	v_mfma_f32_16x16x32_bf16 v[8:11], v[136:139], v[212:215], v[8:11]
	v_mfma_f32_16x16x32_bf16 v[60:63], v[132:135], v[192:195], v[60:63]
	v_mfma_f32_16x16x32_bf16 v[56:59], v[140:143], v[192:195], v[56:59]
	v_mfma_f32_16x16x32_bf16 v[44:47], v[132:135], v[200:203], v[44:47]
	v_mfma_f32_16x16x32_bf16 v[40:43], v[140:143], v[200:203], v[40:43]
	v_mfma_f32_16x16x32_bf16 v[28:31], v[132:135], v[208:211], v[28:31]
	v_mfma_f32_16x16x32_bf16 v[24:27], v[140:143], v[208:211], v[24:27]
	v_mfma_f32_16x16x32_bf16 v[12:15], v[132:135], v[216:219], v[12:15]
	v_mfma_f32_16x16x32_bf16 v[8:11], v[140:143], v[216:219], v[8:11]
	s_setprio 0
	s_setprio 1
	v_mfma_f32_16x16x32_bf16 v[52:55], v[162:165], v[178:181], v[52:55]
	v_mfma_f32_16x16x32_bf16 v[48:51], v[170:173], v[178:181], v[48:51]
	v_mfma_f32_16x16x32_bf16 v[36:39], v[162:165], v[196:199], v[36:39]
	v_mfma_f32_16x16x32_bf16 v[32:35], v[170:173], v[196:199], v[32:35]
	v_mfma_f32_16x16x32_bf16 v[20:23], v[162:165], v[204:207], v[20:23]
	v_mfma_f32_16x16x32_bf16 v[16:19], v[170:173], v[204:207], v[16:19]
	v_mfma_f32_16x16x32_bf16 v[4:7], v[162:165], v[212:215], v[4:7]
	v_mfma_f32_16x16x32_bf16 v[0:3], v[170:173], v[212:215], v[0:3]
	v_mfma_f32_16x16x32_bf16 v[52:55], v[166:169], v[192:195], v[52:55]
	v_mfma_f32_16x16x32_bf16 v[48:51], v[174:177], v[192:195], v[48:51]
	v_mfma_f32_16x16x32_bf16 v[36:39], v[166:169], v[200:203], v[36:39]
	v_mfma_f32_16x16x32_bf16 v[32:35], v[174:177], v[200:203], v[32:35]
	v_mfma_f32_16x16x32_bf16 v[20:23], v[166:169], v[208:211], v[20:23]
	v_mfma_f32_16x16x32_bf16 v[16:19], v[174:177], v[208:211], v[16:19]
	v_mfma_f32_16x16x32_bf16 v[4:7], v[166:169], v[216:219], v[4:7]
	v_mfma_f32_16x16x32_bf16 v[0:3], v[174:177], v[216:219], v[0:3]
	s_barrier
	s_setprio 0
.Lpeel_mid_p4:
	s_add_i32 s57, 0, 0x18000
	s_add_i32 s58, 0, 0x1c000
	v_add_u32_e32 v140, s57, v184
	v_add_u32_e32 v174, s58, v184
	ds_read_b128 v[128:131], v140
	ds_read_b128 v[132:135], v140 offset:1024
	ds_read_b128 v[136:139], v140 offset:2048
	ds_read_b128 v[140:143], v140 offset:3072
	ds_read_b128 v[162:165], v174
	ds_read_b128 v[166:169], v174 offset:1024
	ds_read_b128 v[170:173], v174 offset:2048
	ds_read_b128 v[174:177], v174 offset:3072
	s_add_u32 s40, s40, 0x80000
	s_addc_u32 s41, s41, 0
	s_mov_b32 m0, s44
	v_lshl_add_u64 v[226:227], s[40:41], 0, v[150:151]
	ds_read_b128 v[178:181], v188 offset:32768
	ds_read_b128 v[192:195], v188 offset:33792
	ds_read_b128 v[196:199], v188 offset:34816
	ds_read_b128 v[200:203], v188 offset:35840
	ds_read_b128 v[204:207], v188 offset:36864
	ds_read_b128 v[208:211], v188 offset:37888
	ds_read_b128 v[212:215], v188 offset:38912
	ds_read_b128 v[216:219], v188 offset:39936
	global_load_lds_dwordx4 v[226:227], off
	v_lshl_add_u64 v[226:227], s[40:41], 0, v[146:147]
	s_mov_b32 m0, s45
	s_nop 0
	global_load_lds_dwordx4 v[226:227], off
	s_waitcnt vmcnt(8)
	s_waitcnt lgkmcnt(0)
	s_waitcnt lgkmcnt(0)
	s_setprio 1
	s_barrier
	v_mfma_f32_16x16x32_bf16 v[124:127], v[128:131], v[178:181], v[124:127]
	v_mfma_f32_16x16x32_bf16 v[120:123], v[136:139], v[178:181], v[120:123]
	v_mfma_f32_16x16x32_bf16 v[108:111], v[128:131], v[196:199], v[108:111]
	v_mfma_f32_16x16x32_bf16 v[104:107], v[136:139], v[196:199], v[104:107]
	v_mfma_f32_16x16x32_bf16 v[92:95], v[128:131], v[204:207], v[92:95]
	v_mfma_f32_16x16x32_bf16 v[88:91], v[136:139], v[204:207], v[88:91]
	v_mfma_f32_16x16x32_bf16 v[76:79], v[128:131], v[212:215], v[76:79]
	v_mfma_f32_16x16x32_bf16 v[72:75], v[136:139], v[212:215], v[72:75]
	v_mfma_f32_16x16x32_bf16 v[124:127], v[132:135], v[192:195], v[124:127]
	v_mfma_f32_16x16x32_bf16 v[120:123], v[140:143], v[192:195], v[120:123]
	v_mfma_f32_16x16x32_bf16 v[108:111], v[132:135], v[200:203], v[108:111]
	v_mfma_f32_16x16x32_bf16 v[104:107], v[140:143], v[200:203], v[104:107]
	v_mfma_f32_16x16x32_bf16 v[92:95], v[132:135], v[208:211], v[92:95]
	v_mfma_f32_16x16x32_bf16 v[88:91], v[140:143], v[208:211], v[88:91]
	v_mfma_f32_16x16x32_bf16 v[76:79], v[132:135], v[216:219], v[76:79]
	v_mfma_f32_16x16x32_bf16 v[72:75], v[140:143], v[216:219], v[72:75]
	s_setprio 0
	s_setprio 1
	v_mfma_f32_16x16x32_bf16 v[116:119], v[162:165], v[178:181], v[116:119]
	v_mfma_f32_16x16x32_bf16 v[112:115], v[170:173], v[178:181], v[112:115]
	v_mfma_f32_16x16x32_bf16 v[100:103], v[162:165], v[196:199], v[100:103]
	v_mfma_f32_16x16x32_bf16 v[96:99], v[170:173], v[196:199], v[96:99]
	v_mfma_f32_16x16x32_bf16 v[84:87], v[162:165], v[204:207], v[84:87]
	v_mfma_f32_16x16x32_bf16 v[80:83], v[170:173], v[204:207], v[80:83]
	v_mfma_f32_16x16x32_bf16 v[68:71], v[162:165], v[212:215], v[68:71]
	v_mfma_f32_16x16x32_bf16 v[64:67], v[170:173], v[212:215], v[64:67]
	v_mfma_f32_16x16x32_bf16 v[116:119], v[166:169], v[192:195], v[116:119]
	v_mfma_f32_16x16x32_bf16 v[112:115], v[174:177], v[192:195], v[112:115]
	v_mfma_f32_16x16x32_bf16 v[100:103], v[166:169], v[200:203], v[100:103]
	v_mfma_f32_16x16x32_bf16 v[96:99], v[174:177], v[200:203], v[96:99]
	v_mfma_f32_16x16x32_bf16 v[84:87], v[166:169], v[208:211], v[84:87]
	v_mfma_f32_16x16x32_bf16 v[80:83], v[174:177], v[208:211], v[80:83]
	v_mfma_f32_16x16x32_bf16 v[68:71], v[166:169], v[216:219], v[68:71]
	v_mfma_f32_16x16x32_bf16 v[64:67], v[174:177], v[216:219], v[64:67]
	s_barrier
	s_setprio 0
	s_add_i32 s40, s57, s35
	v_lshl_add_u64 v[182:183], v[182:183], 0, s[14:15]
	s_mov_b32 m0, s40
	ds_read_b128 v[178:181], v188 offset:49152
	ds_read_b128 v[192:195], v188 offset:50176
	ds_read_b128 v[196:199], v188 offset:51200
	ds_read_b128 v[200:203], v188 offset:52224
	ds_read_b128 v[204:207], v188 offset:53248
	ds_read_b128 v[208:211], v188 offset:54272
	ds_read_b128 v[212:215], v188 offset:55296
	ds_read_b128 v[216:219], v188 offset:56320
	global_load_lds_dwordx4 v[182:183], off
	s_add_i32 m0, s40, 0x2000
	s_add_u32 s38, s38, 0x80080
	v_lshl_add_u64 v[182:183], v[220:221], 0, s[14:15]
	s_addc_u32 s39, s39, 0
	s_add_i32 s40, s58, s35
	global_load_lds_dwordx4 v[182:183], off
	v_lshl_add_u64 v[182:183], s[38:39], 0, v[148:149]
	s_mov_b32 m0, s40
	s_nop 0
	global_load_lds_dwordx4 v[182:183], off
	v_lshl_add_u64 v[182:183], s[38:39], 0, v[144:145]
	s_add_i32 m0, s40, 0x2000
	s_nop 0
	global_load_lds_dwordx4 v[182:183], off
	v_lshl_add_u64 v[182:183], v[222:223], 0, s[14:15]
	s_mov_b32 m0, s49
	s_nop 0
	global_load_lds_dwordx4 v[182:183], off
	v_lshl_add_u64 v[182:183], v[224:225], 0, s[14:15]
	s_mov_b32 m0, s50
	s_nop 0
	global_load_lds_dwordx4 v[182:183], off
	s_waitcnt vmcnt(8)
	s_waitcnt lgkmcnt(0)
	s_waitcnt lgkmcnt(0)
	s_setprio 1
	s_barrier
	v_mfma_f32_16x16x32_bf16 v[60:63], v[128:131], v[178:181], v[60:63]
	v_mfma_f32_16x16x32_bf16 v[56:59], v[136:139], v[178:181], v[56:59]
	v_mfma_f32_16x16x32_bf16 v[44:47], v[128:131], v[196:199], v[44:47]
	v_mfma_f32_16x16x32_bf16 v[40:43], v[136:139], v[196:199], v[40:43]
	v_mfma_f32_16x16x32_bf16 v[28:31], v[128:131], v[204:207], v[28:31]
	v_mfma_f32_16x16x32_bf16 v[24:27], v[136:139], v[204:207], v[24:27]
	v_mfma_f32_16x16x32_bf16 v[12:15], v[128:131], v[212:215], v[12:15]
	v_mfma_f32_16x16x32_bf16 v[8:11], v[136:139], v[212:215], v[8:11]
	v_mfma_f32_16x16x32_bf16 v[60:63], v[132:135], v[192:195], v[60:63]
	v_mfma_f32_16x16x32_bf16 v[56:59], v[140:143], v[192:195], v[56:59]
	v_mfma_f32_16x16x32_bf16 v[44:47], v[132:135], v[200:203], v[44:47]
	v_mfma_f32_16x16x32_bf16 v[40:43], v[140:143], v[200:203], v[40:43]
	v_mfma_f32_16x16x32_bf16 v[28:31], v[132:135], v[208:211], v[28:31]
	v_mfma_f32_16x16x32_bf16 v[24:27], v[140:143], v[208:211], v[24:27]
	v_mfma_f32_16x16x32_bf16 v[12:15], v[132:135], v[216:219], v[12:15]
	v_mfma_f32_16x16x32_bf16 v[8:11], v[140:143], v[216:219], v[8:11]
	s_setprio 0
	s_setprio 1
	v_mfma_f32_16x16x32_bf16 v[52:55], v[162:165], v[178:181], v[52:55]
	v_mfma_f32_16x16x32_bf16 v[48:51], v[170:173], v[178:181], v[48:51]
	v_mfma_f32_16x16x32_bf16 v[36:39], v[162:165], v[196:199], v[36:39]
	v_mfma_f32_16x16x32_bf16 v[32:35], v[170:173], v[196:199], v[32:35]
	v_mfma_f32_16x16x32_bf16 v[20:23], v[162:165], v[204:207], v[20:23]
	v_mfma_f32_16x16x32_bf16 v[16:19], v[170:173], v[204:207], v[16:19]
	v_mfma_f32_16x16x32_bf16 v[4:7], v[162:165], v[212:215], v[4:7]
	v_mfma_f32_16x16x32_bf16 v[0:3], v[170:173], v[212:215], v[0:3]
	v_mfma_f32_16x16x32_bf16 v[52:55], v[166:169], v[192:195], v[52:55]
	v_mfma_f32_16x16x32_bf16 v[48:51], v[174:177], v[192:195], v[48:51]
	v_mfma_f32_16x16x32_bf16 v[36:39], v[166:169], v[200:203], v[36:39]
	v_mfma_f32_16x16x32_bf16 v[32:35], v[174:177], v[200:203], v[32:35]
	v_mfma_f32_16x16x32_bf16 v[20:23], v[166:169], v[208:211], v[20:23]
	v_mfma_f32_16x16x32_bf16 v[16:19], v[174:177], v[208:211], v[16:19]
	v_mfma_f32_16x16x32_bf16 v[4:7], v[166:169], v[216:219], v[4:7]
	v_mfma_f32_16x16x32_bf16 v[0:3], v[174:177], v[216:219], v[0:3]
	s_barrier
	s_setprio 0
	s_add_i32 s56, s56, 2
	s_add_u32 s6, s6, 0x100
	s_addc_u32 s7, s7, 0
	s_add_u32 s5, s5, 0x100
	s_addc_u32 s25, s25, 0
	s_cmp_gt_u32 s56, 29
	s_cbranch_scc0 .LBB0_672
	s_and_b64 vcc, exec, s[18:19]
	s_cbranch_vccz .LBB0_675
	s_barrier
